# G2 both layers: token rows of the A tile permuted (stride-8 rows per MFMA lane group) to spread residual/output accesses over L2 channels; l1 epilogue pipelined
# speedup vs baseline: 1.0323x; 1.0073x over previous
; #define PG8_STAGE(bufoff, gbase, voff) do { _Pragma("unroll") for (int _i = 0; _i < 2; ++_i) \
;         __builtin_amdgcn_global_load_lds((const unsigned*)((const char*)(gbase) + (voff)[_i]), (PG8_LAS unsigned*)(lds + (bufoff) + ldsw + _i * 8192), 16, 0, 0); } while (0)
; #define PG8_WAIT_V(n) asm volatile("s_waitcnt vmcnt(" #n ")" ::: "memory")
; #define PG8_BAR __builtin_amdgcn_s_barrier()
; template <class Epi, class Sched, bool ALIGN_EPI = false, bool SP2 = false>
; __device__ __forceinline__ void gemm_phase(PG8_LAS unsigned char* lds, const Gemm g, const Sched& S, const Epi& E) {
;     ...
;     unsigned voffA[2], voffB[2];
; #pragma unroll
;     for (int i = 0; i < 2; ++i) { int R, C; stage_rc(tid * 16 + i * 8192, R, C); const int Rb = Epi::PERM ? ((R & ~31) + perm32(R & 31)) : R;
;         voffA[i] = (unsigned)(R * K + C) * 2u; voffB[i] = (unsigned)(Rb * K + C) * 2u; }
;     ...
;         PG8_STAGE(PG8_SB(0, 0), cB, voffB); PG8_STAGE(PG8_SB(0, 1), cB + hstep, voffB); PG8_STAGE(PG8_SA(0, 0), cA, voffA); PG8_STAGE(PG8_SA(0, 1), cA + hstep, voffA);
;         if (wr == 1) PG8_BAR;
;         PG8_WAIT_V(2); PG8_BAR;
;         PG8_STAGE(PG8_SB(1, 0), cB + kstep, voffB); PG8_STAGE(PG8_SA(1, 0), cA + kstep, voffA); PG8_STAGE(PG8_SB(1, 1), cB + hstep + kstep, voffB);
;         PG8_WAIT_V(6); PG8_BAR;
.LBB0_567:
	v_ashrrev_i32_e32 v1, 31, v8
	v_lshrrev_b32_e32 v1, 26, v1
	v_add_u32_e32 v1, v8, v1
	v_ashrrev_i32_e32 v9, 6, v1
	v_bfe_i32 v1, v8, 27, 1
	v_lshlrev_b32_e32 v0, 4, v8
	v_lshrrev_b32_e32 v1, 22, v1
	v_add_u32_e32 v1, v0, v1
	v_and_b32_e32 v1, 0xfffffc00, v1
	v_sub_u32_e32 v1, v0, v1
	v_lshrrev_b32_e32 v2, 4, v1
	v_bitop3_b32 v1, v2, v1, 32 bitop3:0x6c
	v_ashrrev_i32_e32 v3, 31, v1
	v_lshrrev_b32_e32 v3, 26, v3
	s_waitcnt lgkmcnt(0)
	s_add_u32 s40, s10, 0x1600000
	v_add_u32_e32 v3, v1, v3
	s_addc_u32 s41, s11, 0
	v_ashrrev_i32_e32 v10, 6, v3
	v_and_b32_e32 v3, 0xc0, v3
	s_add_u32 s42, s10, 0x2000000
	v_sub_u32_e32 v1, v1, v3
	v_mov_b32_e32 v3, 1
	s_addc_u32 s43, s11, 0
	v_lshlrev_b32_e32 v2, 3, v9
	v_lshlrev_b32_e32 v4, 5, v9
	v_ashrrev_i16_sdwa v1, v3, sext(v1) dst_sel:DWORD dst_unused:UNUSED_PAD src0_sel:DWORD src1_sel:BYTE_0
	s_add_i32 s4, s6, s4
	v_and_b32_e32 v2, 0x1ffff0, v2
	v_and_b32_e32 v4, 32, v4
	v_bfe_i32 v11, v1, 0, 16
	s_ashr_i32 s6, s4, 31
	v_add_u32_e32 v1, v4, v11
	v_add_lshl_u32 v2, v10, v2, 11
	v_add_u32_e32 v0, 0x2000, v0
	s_lshr_b32 s6, s6, 27
	v_lshl_add_u32 v144, v1, 1, v2
	v_ashrrev_i32_e32 v1, 31, v0
	s_add_i32 s6, s4, s6
	v_lshrrev_b32_e32 v1, 22, v1
	s_ashr_i32 s7, s6, 5
	s_and_b32 s6, s6, 0xffe0
	v_add_u32_e32 v1, v0, v1
	s_sub_i32 s6, s4, s6
	v_ashrrev_i32_e32 v12, 10, v1
	s_bfe_i32 s4, s6, 0x80000
	v_mul_i32_i24_e32 v1, 0x400, v12
	s_bfe_u32 s4, s4, 0x3000c
	v_sub_u32_e32 v0, v0, v1
	s_add_i32 s14, s6, s4
	v_lshrrev_b32_e32 v1, 4, v0
	s_bfe_i32 s4, s14, 0x80000
	s_and_b32 s14, s14, 0xf8
	v_bitop3_b32 v0, v1, v0, 32 bitop3:0x6c
	s_sub_i32 s6, s6, s14
	v_ashrrev_i32_e32 v2, 31, v0
	s_lshl_b32 s7, s7, 3
	s_sext_i32_i16 s4, s4
	s_sext_i32_i8 s6, s6
	s_ashr_i32 s5, s12, 8
	v_lshrrev_b32_e32 v2, 26, v2
	s_lshr_b32 s4, s4, 3
	s_add_i32 s30, s7, s6
	v_add_u32_e32 v2, v0, v2
	s_ashr_i32 s13, s12, 6
	s_ashr_i32 s31, s30, 31
	s_bfe_i64 s[14:15], s[4:5], 0x100000
	v_ashrrev_i32_e32 v13, 6, v2
	v_and_b32_e32 v2, 0xc0, v2
	s_lshl_b32 s44, s13, 10
	s_lshl_b64 s[6:7], s[30:31], 19
	s_lshl_b64 s[14:15], s[14:15], 19
	v_sub_u32_e32 v0, v0, v2
	s_add_u32 s34, s40, s14
	v_lshlrev_b32_e32 v1, 3, v12
	v_lshlrev_b32_e32 v4, 5, v12
	v_ashrrev_i16_sdwa v0, v3, sext(v0) dst_sel:DWORD dst_unused:UNUSED_PAD src0_sel:DWORD src1_sel:BYTE_0
	s_addc_u32 s35, s41, s15
	s_add_i32 s31, s44, 0
	v_and_b32_e32 v1, 0x1ffff0, v1
	v_and_b32_e32 v4, 32, v4
	v_bfe_i32 v14, v0, 0, 16
	s_add_i32 m0, s31, 0x10000
	v_add_u32_e32 v0, v4, v14
	v_add_lshl_u32 v1, v13, v1, 11
	global_load_lds_dwordx4 v144, s[34:35]
	s_add_i32 m0, s31, 0x12000
	v_lshl_add_u32 v146, v0, 1, v1
	v_lshrrev_b32_e32 v222, 11, v144
	v_and_b32_e32 v223, 15, v222
	v_lshlrev_b32_e32 v223, 3, v223
	v_bfe_u32 v150, v222, 6, 1
	v_lshl_or_b32 v223, v150, 2, v223
	v_bfe_u32 v150, v222, 4, 2
	v_or_b32_e32 v223, v223, v150
	v_and_b32_e32 v150, 0x7ff, v144
	v_lshl_or_b32 v150, v223, 11, v150
	v_lshrrev_b32_e32 v222, 11, v146
	v_and_b32_e32 v223, 15, v222
	v_lshlrev_b32_e32 v223, 3, v223
	v_bfe_u32 v148, v222, 6, 1
	v_lshl_or_b32 v223, v148, 2, v223
	v_bfe_u32 v148, v222, 4, 2
	v_or_b32_e32 v223, v223, v148
	v_and_b32_e32 v148, 0x7ff, v146
	v_lshl_or_b32 v148, v223, 11, v148
	v_mov_b32_e32 v149, 0
	v_mov_b32_e32 v151, 0
	s_add_u32 s14, s34, 0x40000
	global_load_lds_dwordx4 v146, s[34:35]
	s_addc_u32 s15, s35, 0
	s_add_i32 m0, s31, 0x14000
	s_load_dwordx2 s[0:1], s[0:1], 0x0
	global_load_lds_dwordx4 v144, s[14:15]
	s_add_i32 m0, s31, 0x16000
	s_add_u32 s36, s42, s6
	s_addc_u32 s37, s43, s7
	s_add_i32 s45, s31, 0x2000
	global_load_lds_dwordx4 v146, s[14:15]
	s_mov_b32 m0, s31
	s_add_u32 s6, s36, 0x40000
	global_load_lds_dwordx4 v150, s[36:37]
	s_mov_b32 m0, s45
	s_addc_u32 s7, s37, 0
	s_add_i32 s46, s31, 0x4000
	global_load_lds_dwordx4 v148, s[36:37]
	s_mov_b32 m0, s46
	s_add_i32 s47, s31, 0x6000
	global_load_lds_dwordx4 v150, s[6:7]
	s_mov_b32 m0, s47
	v_mov_b32_e32 v145, 0
	global_load_lds_dwordx4 v148, s[6:7]
	v_mov_b32_e32 v147, v145
	s_cmp_eq_u32 s5, 1
	s_mov_b32 s48, 0
	v_lshl_add_u64 v[6:7], s[34:35], 0, v[144:145]
	v_lshl_add_u64 v[4:5], s[34:35], 0, v[146:147]
	v_lshl_add_u64 v[0:1], s[36:37], 0, v[150:151]
	s_cselect_b64 s[6:7], -1, 0
	s_cmp_lg_u32 s5, 1
	v_lshl_add_u64 v[2:3], s[36:37], 0, v[148:149]
	s_cbranch_scc1 .LBB0_569
	s_barrier
.LBB0_569:
	s_add_u32 s49, s10, 0x102000
	s_addc_u32 s50, s11, 0
	s_lshl_b32 s10, s13, 5
	s_and_b32 s17, s10, 0x60
	s_mov_b64 s[10:11], 0x80
	s_add_i32 m0, s31, 0x18000
	v_lshl_add_u64 v[6:7], v[6:7], 0, s[10:11]
	s_lshl_b32 s16, s5, 13
	s_lshl_b32 s13, s17, 7
	s_waitcnt vmcnt(2)
	s_barrier
	global_load_lds_dwordx4 v[6:7], off
	v_lshl_add_u64 v[4:5], v[4:5], 0, s[10:11]
	s_add_i32 m0, s31, 0x1a000
	s_add_i32 s51, s31, 0x8000
	s_add_i32 s52, s31, 0xa000
	global_load_lds_dwordx4 v[4:5], off
	v_lshl_add_u64 v[0:1], v[0:1], 0, s[10:11]
	s_mov_b32 m0, s51
	s_add_u32 s14, s34, 0x40080
	global_load_lds_dwordx4 v[0:1], off
	v_lshl_add_u64 v[0:1], v[2:3], 0, s[10:11]
	s_mov_b32 m0, s52
	s_addc_u32 s15, s35, 0
	global_load_lds_dwordx4 v[0:1], off
	s_add_i32 m0, s31, 0x1c000
	v_lshl_add_u64 v[0:1], s[14:15], 0, v[144:145]
	global_load_lds_dwordx4 v[0:1], off
	v_lshl_add_u64 v[0:1], s[14:15], 0, v[146:147]
	s_add_i32 m0, s31, 0x1e000
	s_cmpk_lt_u32 s12, 0x100
	global_load_lds_dwordx4 v[0:1], off
	v_bfe_u32 v1, v8, 4, 2
	v_and_b32_e32 v0, 15, v8
	v_lshlrev_b32_e32 v2, 4, v1
	v_lshl_or_b32 v158, s5, 6, v0
	v_lshl_or_b32 v0, v0, 6, v2
	v_lshlrev_b32_e32 v2, 2, v8
	v_and_b32_e32 v2, 32, v2
	v_bitop3_b32 v3, v0, s16, v2 bitop3:0xde
	v_bitop3_b32 v159, v0, s13, v2 bitop3:0xde
	v_lshlrev_b32_e32 v0, 14, v12
	v_and_b32_e32 v0, 0xffff8000, v0
	v_lshl_or_b32 v160, v1, 2, s17
	v_lshl_add_u32 v0, v13, 11, v0
	v_and_b32_e32 v1, 1, v12
	v_lshl_or_b32 v0, v1, 6, v0
	s_nop 0
	v_lshlrev_b32_e32 v0, 14, v9
	v_and_b32_e32 v0, 0xffff8000, v0
	s_waitcnt vmcnt(6)
	v_lshl_add_u32 v0, v10, 11, v0
	v_and_b32_e32 v1, 1, v9
	s_cselect_b64 s[12:13], -1, 0
	v_lshl_or_b32 v0, v1, 6, v0
	s_add_i32 s54, 0, 0x10000
	s_add_i32 s55, 0, 0x14000
	s_sext_i32_i8 s56, s4
	s_ashr_i32 s53, s3, 31
	v_mov_b32_e32 v149, v145
	s_nop 0
	v_mov_b32_e32 v151, v145
	v_mov_b64_e32 v[152:153], 0x400
	v_mov_b64_e32 v[154:155], 0x3ff
	v_add_u32_e32 v161, s54, v159
	v_add_u32_e32 v162, s55, v159
	v_add_u32_e32 v163, 0, v3
	s_mov_b64 s[14:15], 0x80000
	s_mov_b64 s[16:17], 0x90000
	s_mov_b64 s[18:19], 0xa0000
	s_mov_b64 s[20:21], 0xb0000
	s_barrier
	s_branch .LBB0_572

; #define PG8_STAGE(bufoff, gbase, voff) do { _Pragma("unroll") for (int _i = 0; _i < 2; ++_i) \
;         __builtin_amdgcn_global_load_lds((const unsigned*)((const char*)(gbase) + (voff)[_i]), (PG8_LAS unsigned*)(lds + (bufoff) + ldsw + _i * 8192), 16, 0, 0); } while (0)
; #define PG8_LDA(dst, b, h) do { _Pragma("unroll") for (int m = 0; m < 4; ++m) _Pragma("unroll") for (int k = 0; k < 2; ++k) dst[m][k] = *(const PG8_LAS bf16x8*)(lds + PG8_SA(b, h) + aoff + m * 2048 + k * 1024); } while (0)
; #define PG8_LDB(dst, b, h) do { _Pragma("unroll") for (int n = 0; n < 2; ++n) _Pragma("unroll") for (int k = 0; k < 2; ++k) dst[n][k] = *(const PG8_LAS bf16x8*)(lds + PG8_SB(b, h) + boff + n * 2048 + k * 1024); } while (0)
; #define PG8_MMA(ai, bj, At, Bt) do { __builtin_amdgcn_s_setprio(1); _Pragma("unroll") for (int m = 0; m < 4; ++m) _Pragma("unroll") for (int n = 0; n < 2; ++n) _Pragma("unroll") for (int k = 0; k < 2; ++k) \
;         acc[ai][bj][m][n] = __builtin_amdgcn_mfma_f32_16x16x32_bf16(Bt[n][k], At[m][k], acc[ai][bj][m][n], 0, 0, 0); __builtin_amdgcn_s_setprio(0); } while (0)
; #define PG8_WAIT_V(n) asm volatile("s_waitcnt vmcnt(" #n ")" ::: "memory")
; #define PG8_WAIT_L(n) asm volatile("s_waitcnt lgkmcnt(" #n ")" ::: "memory")
; #define PG8_BAR __builtin_amdgcn_s_barrier()
; #define PG8_SCHED __builtin_amdgcn_sched_barrier(0)
; template <class Epi, class Sched, bool ALIGN_EPI = false, bool SP2 = false>
; __device__ __forceinline__ void gemm_phase(PG8_LAS unsigned char* lds, const Gemm g, const Sched& S, const Epi& E) {
;     ...
;             PG8_LDB(B0, 0, 0); PG8_LDB(B1, 0, 1); PG8_SCHED; PG8_LDA(At, 0, 0); PG8_STAGE(PG8_SA(1, 1), a1 + hstep, voffA);
;             PG8_WAIT_V(8); PG8_WAIT_L(0); PG8_BAR; PG8_MMA(0, 0, At, B0); PG8_MMA(0, 1, At, B1); PG8_BAR; PG8_SCHED;
;             PG8_LDA(At, 0, 1); PG8_STAGE(PG8_SB(0, 0), b2, voffB); PG8_STAGE(PG8_SB(0, 1), b2 + hstep, voffB); PG8_STAGE(PG8_SA(0, 0), a2, voffA);
;             PG8_WAIT_V(8); PG8_WAIT_L(0); PG8_BAR; PG8_MMA(1, 0, At, B0); PG8_MMA(1, 1, At, B1); PG8_BAR; PG8_SCHED;
.LBB0_579:
	ds_read_b128 v[128:131], v161
	ds_read_b128 v[132:135], v161 offset:1024
	ds_read_b128 v[136:139], v161 offset:2048
	ds_read_b128 v[140:143], v161 offset:3072
	ds_read_b128 v[164:167], v162
	ds_read_b128 v[168:171], v162 offset:1024
	ds_read_b128 v[172:175], v162 offset:2048
	ds_read_b128 v[176:179], v162 offset:3072
	s_add_u32 s36, s34, 0xfffc0080
	s_addc_u32 s37, s35, -1
	s_cmp_eq_u32 s61, 12
	s_cselect_b32 s39, s25, s37
	s_cselect_b32 s38, s57, s36
	s_cselect_b32 s37, s23, s60
	s_cselect_b32 s36, s58, s59
	v_lshl_add_u64 v[156:157], s[34:35], 0, v[150:151]
	s_add_i32 m0, s31, 0xc000
	ds_read_b128 v[180:183], v163
	ds_read_b128 v[184:187], v163 offset:1024
	ds_read_b128 v[188:191], v163 offset:2048
	ds_read_b128 v[192:195], v163 offset:3072
	ds_read_b128 v[196:199], v163 offset:4096
	ds_read_b128 v[204:207], v163 offset:5120
	ds_read_b128 v[208:211], v163 offset:6144
	ds_read_b128 v[212:215], v163 offset:7168
	global_load_lds_dwordx4 v[156:157], off
	v_lshl_add_u64 v[156:157], s[34:35], 0, v[148:149]
	s_add_i32 m0, s31, 0xe000
	s_nop 0
	global_load_lds_dwordx4 v[156:157], off
	s_waitcnt vmcnt(8)
	s_waitcnt lgkmcnt(0)
	s_barrier
	s_setprio 1
	s_waitcnt lgkmcnt(0)
	v_mfma_f32_16x16x32_bf16 v[124:127], v[128:131], v[180:183], v[124:127]
	v_mfma_f32_16x16x32_bf16 v[120:123], v[136:139], v[180:183], v[120:123]
	v_mfma_f32_16x16x32_bf16 v[112:115], v[128:131], v[188:191], v[112:115]
	v_mfma_f32_16x16x32_bf16 v[108:111], v[136:139], v[188:191], v[108:111]
	v_mfma_f32_16x16x32_bf16 v[96:99], v[128:131], v[196:199], v[96:99]
	v_mfma_f32_16x16x32_bf16 v[92:95], v[136:139], v[196:199], v[92:95]
	v_mfma_f32_16x16x32_bf16 v[80:83], v[128:131], v[208:211], v[80:83]
	v_mfma_f32_16x16x32_bf16 v[76:79], v[136:139], v[208:211], v[76:79]
	v_mfma_f32_16x16x32_bf16 v[124:127], v[132:135], v[184:187], v[124:127]
	v_mfma_f32_16x16x32_bf16 v[120:123], v[140:143], v[184:187], v[120:123]
	v_mfma_f32_16x16x32_bf16 v[112:115], v[132:135], v[192:195], v[112:115]
	v_mfma_f32_16x16x32_bf16 v[108:111], v[140:143], v[192:195], v[108:111]
	v_mfma_f32_16x16x32_bf16 v[96:99], v[132:135], v[204:207], v[96:99]
	v_mfma_f32_16x16x32_bf16 v[92:95], v[140:143], v[204:207], v[92:95]
	v_mfma_f32_16x16x32_bf16 v[80:83], v[132:135], v[212:215], v[80:83]
	v_mfma_f32_16x16x32_bf16 v[76:79], v[140:143], v[212:215], v[76:79]
	s_setprio 0
	s_setprio 1
	v_mfma_f32_16x16x32_bf16 v[116:119], v[164:167], v[180:183], v[116:119]
	v_mfma_f32_16x16x32_bf16 v[104:107], v[172:175], v[180:183], v[104:107]
	v_mfma_f32_16x16x32_bf16 v[100:103], v[164:167], v[188:191], v[100:103]
	v_mfma_f32_16x16x32_bf16 v[88:91], v[172:175], v[188:191], v[88:91]
	v_mfma_f32_16x16x32_bf16 v[84:87], v[164:167], v[196:199], v[84:87]
	v_mfma_f32_16x16x32_bf16 v[72:75], v[172:175], v[196:199], v[72:75]
	v_mfma_f32_16x16x32_bf16 v[68:71], v[164:167], v[208:211], v[68:71]
	v_mfma_f32_16x16x32_bf16 v[64:67], v[172:175], v[208:211], v[64:67]
	v_mfma_f32_16x16x32_bf16 v[116:119], v[168:171], v[184:187], v[116:119]
	v_mfma_f32_16x16x32_bf16 v[104:107], v[176:179], v[184:187], v[104:107]
	v_mfma_f32_16x16x32_bf16 v[100:103], v[168:171], v[192:195], v[100:103]
	v_mfma_f32_16x16x32_bf16 v[88:91], v[176:179], v[192:195], v[88:91]
	v_mfma_f32_16x16x32_bf16 v[84:87], v[168:171], v[204:207], v[84:87]
	v_mfma_f32_16x16x32_bf16 v[72:75], v[176:179], v[204:207], v[72:75]
	v_mfma_f32_16x16x32_bf16 v[68:71], v[168:171], v[212:215], v[68:71]
	v_mfma_f32_16x16x32_bf16 v[64:67], v[176:179], v[212:215], v[64:67]
	s_setprio 0
	s_barrier
	s_add_i32 s62, s54, s44
	v_lshl_add_u64 v[156:157], s[36:37], 0, v[144:145]
	s_mov_b32 m0, s62
	ds_read_b128 v[180:183], v163 offset:16384
	ds_read_b128 v[184:187], v163 offset:17408
	ds_read_b128 v[188:191], v163 offset:18432
	ds_read_b128 v[192:195], v163 offset:19456
	ds_read_b128 v[196:199], v163 offset:20480
	ds_read_b128 v[204:207], v163 offset:21504
	ds_read_b128 v[208:211], v163 offset:22528
	ds_read_b128 v[212:215], v163 offset:23552
	global_load_lds_dwordx4 v[156:157], off
	s_add_i32 m0, s62, 0x2000
	s_add_u32 s62, s36, 0x40000
	v_lshl_add_u64 v[200:201], s[36:37], 0, v[146:147]
	s_addc_u32 s63, s37, 0
	s_add_i32 s64, s55, s44
	global_load_lds_dwordx4 v[200:201], off
	v_lshl_add_u64 v[216:217], s[62:63], 0, v[144:145]
	s_mov_b32 m0, s64
	v_lshl_add_u64 v[218:219], s[38:39], 0, v[148:149]
	global_load_lds_dwordx4 v[216:217], off
	v_lshl_add_u64 v[216:217], s[62:63], 0, v[146:147]
	s_add_i32 m0, s64, 0x2000
	s_nop 0
	global_load_lds_dwordx4 v[216:217], off
	v_lshl_add_u64 v[216:217], s[38:39], 0, v[150:151]
	s_mov_b32 m0, s31
	s_nop 0
	global_load_lds_dwordx4 v[216:217], off
	s_mov_b32 m0, s45
	s_nop 0
	global_load_lds_dwordx4 v[218:219], off
	s_waitcnt vmcnt(8)
	s_waitcnt lgkmcnt(0)
	s_barrier
; #define PG8_STAGE(bufoff, gbase, voff) do { _Pragma("unroll") for (int _i = 0; _i < 2; ++_i) \
;         __builtin_amdgcn_global_load_lds((const unsigned*)((const char*)(gbase) + (voff)[_i]), (PG8_LAS unsigned*)(lds + (bufoff) + ldsw + _i * 8192), 16, 0, 0); } while (0)
; #define PG8_LDA(dst, b, h) do { _Pragma("unroll") for (int m = 0; m < 4; ++m) _Pragma("unroll") for (int k = 0; k < 2; ++k) dst[m][k] = *(const PG8_LAS bf16x8*)(lds + PG8_SA(b, h) + aoff + m * 2048 + k * 1024); } while (0)
; #define PG8_LDB(dst, b, h) do { _Pragma("unroll") for (int n = 0; n < 2; ++n) _Pragma("unroll") for (int k = 0; k < 2; ++k) dst[n][k] = *(const PG8_LAS bf16x8*)(lds + PG8_SB(b, h) + boff + n * 2048 + k * 1024); } while (0)
; #define PG8_MMA(ai, bj, At, Bt) do { __builtin_amdgcn_s_setprio(1); _Pragma("unroll") for (int m = 0; m < 4; ++m) _Pragma("unroll") for (int n = 0; n < 2; ++n) _Pragma("unroll") for (int k = 0; k < 2; ++k) \
;         acc[ai][bj][m][n] = __builtin_amdgcn_mfma_f32_16x16x32_bf16(Bt[n][k], At[m][k], acc[ai][bj][m][n], 0, 0, 0); __builtin_amdgcn_s_setprio(0); } while (0)
; #define PG8_WAIT_V(n) asm volatile("s_waitcnt vmcnt(" #n ")" ::: "memory")
; #define PG8_WAIT_L(n) asm volatile("s_waitcnt lgkmcnt(" #n ")" ::: "memory")
; #define PG8_BAR __builtin_amdgcn_s_barrier()
; #define PG8_SCHED __builtin_amdgcn_sched_barrier(0)
; template <class Epi, class Sched, bool ALIGN_EPI = false, bool SP2 = false>
; __device__ __forceinline__ void gemm_phase(PG8_LAS unsigned char* lds, const Gemm g, const Sched& S, const Epi& E) {
;     ...
;             PG8_WAIT_V(8); PG8_WAIT_L(0); PG8_BAR; PG8_MMA(1, 0, At, B0); PG8_MMA(1, 1, At, B1); PG8_BAR; PG8_SCHED;
;             PG8_LDB(B0, 1, 0); PG8_LDB(B1, 1, 1); PG8_SCHED; PG8_LDA(At, 1, 0); PG8_STAGE(PG8_SA(0, 1), a2 + hstep, voffA);
;             PG8_WAIT_V(8); PG8_WAIT_L(0); PG8_BAR; PG8_MMA(0, 0, At, B0); PG8_MMA(0, 1, At, B1); PG8_BAR; PG8_SCHED;
	s_setprio 1
	s_waitcnt lgkmcnt(0)
	v_mfma_f32_16x16x32_bf16 v[60:63], v[128:131], v[180:183], v[60:63]
	v_mfma_f32_16x16x32_bf16 v[56:59], v[136:139], v[180:183], v[56:59]
	v_mfma_f32_16x16x32_bf16 v[48:51], v[128:131], v[188:191], v[48:51]
	v_mfma_f32_16x16x32_bf16 v[44:47], v[136:139], v[188:191], v[44:47]
	v_mfma_f32_16x16x32_bf16 v[32:35], v[128:131], v[196:199], v[32:35]
	v_mfma_f32_16x16x32_bf16 v[28:31], v[136:139], v[196:199], v[28:31]
	v_mfma_f32_16x16x32_bf16 v[16:19], v[128:131], v[208:211], v[16:19]
	v_mfma_f32_16x16x32_bf16 v[12:15], v[136:139], v[208:211], v[12:15]
	v_mfma_f32_16x16x32_bf16 v[60:63], v[132:135], v[184:187], v[60:63]
	v_mfma_f32_16x16x32_bf16 v[56:59], v[140:143], v[184:187], v[56:59]
	v_mfma_f32_16x16x32_bf16 v[48:51], v[132:135], v[192:195], v[48:51]
	v_mfma_f32_16x16x32_bf16 v[44:47], v[140:143], v[192:195], v[44:47]
	v_mfma_f32_16x16x32_bf16 v[32:35], v[132:135], v[204:207], v[32:35]
	v_mfma_f32_16x16x32_bf16 v[28:31], v[140:143], v[204:207], v[28:31]
	v_mfma_f32_16x16x32_bf16 v[16:19], v[132:135], v[212:215], v[16:19]
	v_mfma_f32_16x16x32_bf16 v[12:15], v[140:143], v[212:215], v[12:15]
	s_setprio 0
	s_setprio 1
	v_mfma_f32_16x16x32_bf16 v[52:55], v[164:167], v[180:183], v[52:55]
	v_mfma_f32_16x16x32_bf16 v[40:43], v[172:175], v[180:183], v[40:43]
	v_mfma_f32_16x16x32_bf16 v[36:39], v[164:167], v[188:191], v[36:39]
	v_mfma_f32_16x16x32_bf16 v[24:27], v[172:175], v[188:191], v[24:27]
	v_mfma_f32_16x16x32_bf16 v[20:23], v[164:167], v[196:199], v[20:23]
	v_mfma_f32_16x16x32_bf16 v[8:11], v[172:175], v[196:199], v[8:11]
	v_mfma_f32_16x16x32_bf16 v[4:7], v[164:167], v[208:211], v[4:7]
	v_mfma_f32_16x16x32_bf16 v[0:3], v[172:175], v[208:211], v[0:3]
	v_mfma_f32_16x16x32_bf16 v[52:55], v[168:171], v[184:187], v[52:55]
	v_mfma_f32_16x16x32_bf16 v[40:43], v[176:179], v[184:187], v[40:43]
	v_mfma_f32_16x16x32_bf16 v[36:39], v[168:171], v[192:195], v[36:39]
	v_mfma_f32_16x16x32_bf16 v[24:27], v[176:179], v[192:195], v[24:27]
	v_mfma_f32_16x16x32_bf16 v[20:23], v[168:171], v[204:207], v[20:23]
	v_mfma_f32_16x16x32_bf16 v[8:11], v[176:179], v[204:207], v[8:11]
	v_mfma_f32_16x16x32_bf16 v[4:7], v[168:171], v[212:215], v[4:7]
	v_mfma_f32_16x16x32_bf16 v[0:3], v[176:179], v[212:215], v[0:3]
	s_setprio 0
	s_barrier
	s_add_i32 s62, 0, 0x18000
	s_add_i32 s63, 0, 0x1c000
	v_add_u32_e32 v140, s62, v159
	v_add_u32_e32 v176, s63, v159
	ds_read_b128 v[128:131], v140
	ds_read_b128 v[132:135], v140 offset:1024
	ds_read_b128 v[136:139], v140 offset:2048
	ds_read_b128 v[140:143], v140 offset:3072
	ds_read_b128 v[164:167], v176
	ds_read_b128 v[168:171], v176 offset:1024
	ds_read_b128 v[172:175], v176 offset:2048
	ds_read_b128 v[176:179], v176 offset:3072
	s_add_u32 s38, s38, 0x40000
	s_addc_u32 s39, s39, 0
	s_mov_b32 m0, s46
	v_lshl_add_u64 v[220:221], s[38:39], 0, v[150:151]
	ds_read_b128 v[180:183], v163 offset:32768
	ds_read_b128 v[184:187], v163 offset:33792
	ds_read_b128 v[188:191], v163 offset:34816
	ds_read_b128 v[192:195], v163 offset:35840
	ds_read_b128 v[196:199], v163 offset:36864
	ds_read_b128 v[204:207], v163 offset:37888
	ds_read_b128 v[208:211], v163 offset:38912
	ds_read_b128 v[212:215], v163 offset:39936
	global_load_lds_dwordx4 v[220:221], off
	v_lshl_add_u64 v[220:221], s[38:39], 0, v[148:149]
	s_mov_b32 m0, s47
	s_nop 0
	global_load_lds_dwordx4 v[220:221], off
	s_waitcnt vmcnt(8)
	s_waitcnt lgkmcnt(0)
	s_barrier
	s_setprio 1
	s_waitcnt lgkmcnt(0)
	v_mfma_f32_16x16x32_bf16 v[124:127], v[128:131], v[180:183], v[124:127]
	v_mfma_f32_16x16x32_bf16 v[120:123], v[136:139], v[180:183], v[120:123]
	v_mfma_f32_16x16x32_bf16 v[112:115], v[128:131], v[188:191], v[112:115]
	v_mfma_f32_16x16x32_bf16 v[108:111], v[136:139], v[188:191], v[108:111]
	v_mfma_f32_16x16x32_bf16 v[96:99], v[128:131], v[196:199], v[96:99]
	v_mfma_f32_16x16x32_bf16 v[92:95], v[136:139], v[196:199], v[92:95]
	v_mfma_f32_16x16x32_bf16 v[80:83], v[128:131], v[208:211], v[80:83]
	v_mfma_f32_16x16x32_bf16 v[76:79], v[136:139], v[208:211], v[76:79]
	v_mfma_f32_16x16x32_bf16 v[124:127], v[132:135], v[184:187], v[124:127]
	v_mfma_f32_16x16x32_bf16 v[120:123], v[140:143], v[184:187], v[120:123]
	v_mfma_f32_16x16x32_bf16 v[112:115], v[132:135], v[192:195], v[112:115]
	v_mfma_f32_16x16x32_bf16 v[108:111], v[140:143], v[192:195], v[108:111]
	v_mfma_f32_16x16x32_bf16 v[96:99], v[132:135], v[204:207], v[96:99]
	v_mfma_f32_16x16x32_bf16 v[92:95], v[140:143], v[204:207], v[92:95]
	v_mfma_f32_16x16x32_bf16 v[80:83], v[132:135], v[212:215], v[80:83]
	v_mfma_f32_16x16x32_bf16 v[76:79], v[140:143], v[212:215], v[76:79]
	s_setprio 0
	s_setprio 1
	v_mfma_f32_16x16x32_bf16 v[116:119], v[164:167], v[180:183], v[116:119]
	v_mfma_f32_16x16x32_bf16 v[104:107], v[172:175], v[180:183], v[104:107]
	v_mfma_f32_16x16x32_bf16 v[100:103], v[164:167], v[188:191], v[100:103]
	v_mfma_f32_16x16x32_bf16 v[88:91], v[172:175], v[188:191], v[88:91]
	v_mfma_f32_16x16x32_bf16 v[84:87], v[164:167], v[196:199], v[84:87]
	v_mfma_f32_16x16x32_bf16 v[72:75], v[172:175], v[196:199], v[72:75]
	v_mfma_f32_16x16x32_bf16 v[68:71], v[164:167], v[208:211], v[68:71]
	v_mfma_f32_16x16x32_bf16 v[64:67], v[172:175], v[208:211], v[64:67]
	v_mfma_f32_16x16x32_bf16 v[116:119], v[168:171], v[184:187], v[116:119]
	v_mfma_f32_16x16x32_bf16 v[104:107], v[176:179], v[184:187], v[104:107]
	v_mfma_f32_16x16x32_bf16 v[100:103], v[168:171], v[192:195], v[100:103]
	v_mfma_f32_16x16x32_bf16 v[88:91], v[176:179], v[192:195], v[88:91]
	v_mfma_f32_16x16x32_bf16 v[84:87], v[168:171], v[204:207], v[84:87]
	v_mfma_f32_16x16x32_bf16 v[72:75], v[176:179], v[204:207], v[72:75]
	v_mfma_f32_16x16x32_bf16 v[68:71], v[168:171], v[212:215], v[68:71]
	v_mfma_f32_16x16x32_bf16 v[64:67], v[176:179], v[212:215], v[64:67]
	s_setprio 0
	s_barrier
; #define PG8_STAGE(bufoff, gbase, voff) do { _Pragma("unroll") for (int _i = 0; _i < 2; ++_i) \
;         __builtin_amdgcn_global_load_lds((const unsigned*)((const char*)(gbase) + (voff)[_i]), (PG8_LAS unsigned*)(lds + (bufoff) + ldsw + _i * 8192), 16, 0, 0); } while (0)
; #define PG8_LDA(dst, b, h) do { _Pragma("unroll") for (int m = 0; m < 4; ++m) _Pragma("unroll") for (int k = 0; k < 2; ++k) dst[m][k] = *(const PG8_LAS bf16x8*)(lds + PG8_SA(b, h) + aoff + m * 2048 + k * 1024); } while (0)
; #define PG8_MMA(ai, bj, At, Bt) do { __builtin_amdgcn_s_setprio(1); _Pragma("unroll") for (int m = 0; m < 4; ++m) _Pragma("unroll") for (int n = 0; n < 2; ++n) _Pragma("unroll") for (int k = 0; k < 2; ++k) \
;         acc[ai][bj][m][n] = __builtin_amdgcn_mfma_f32_16x16x32_bf16(Bt[n][k], At[m][k], acc[ai][bj][m][n], 0, 0, 0); __builtin_amdgcn_s_setprio(0); } while (0)
; #define PG8_WAIT_V(n) asm volatile("s_waitcnt vmcnt(" #n ")" ::: "memory")
; #define PG8_BAR __builtin_amdgcn_s_barrier()
; template <class Epi, class Sched, bool ALIGN_EPI = false, bool SP2 = false>
; __device__ __forceinline__ void gemm_phase(PG8_LAS unsigned char* lds, const Gemm g, const Sched& S, const Epi& E) {
;     ...
;             PG8_LDA(At, 1, 1); PG8_STAGE(PG8_SB(1, 0), b3, voffB); PG8_STAGE(PG8_SB(1, 1), b3 + hstep, voffB); PG8_STAGE(PG8_SA(1, 0), a3, voffA);
;             PG8_WAIT_V(8); PG8_WAIT_L(0); PG8_BAR; PG8_MMA(1, 0, At, B0); PG8_MMA(1, 1, At, B1); PG8_BAR; PG8_SCHED;
;     __device__ __forceinline__ void operator()(const f32x4 (&acc)[2][2][4][2], const pg8::Unit& u, int wr, int wc, int fr, int fq) const {
;         const int row0 = u.pm * 256 + wr * 64 + fr, col0 = u.pn * 256 + wc * 32 + 4 * fq;
;         const float* gp = gatev + (size_t)(u.pm >> 3) * 3072 + col0;
;         f32x4 gv[2][2];
; #pragma unroll
;         for (int bj = 0; bj < 2; ++bj)
; #pragma unroll
;             for (int n = 0; n < 2; ++n) gv[bj][n] = *(const f32x4*)(gp + bj * 128 + n * 16);
; #pragma unroll
;         for (int ai = 0; ai < 2; ++ai)
; #pragma unroll
;             for (int m = 0; m < 4; ++m) {
;                 const size_t off = (size_t)(row0 + ai * 128 + m * 16) * DM + col0;
; #pragma unroll
;                 for (int bj = 0; bj < 2; ++bj)
; #pragma unroll
;                     for (int n = 0; n < 2; ++n) {
;                         const f32x4 xv = *(const f32x4*)(xin + off + bj * 128 + n * 16);
	s_add_i32 s38, s62, s44
	v_lshl_add_u64 v[156:157], v[156:157], 0, s[10:11]
	s_mov_b32 m0, s38
	ds_read_b128 v[180:183], v163 offset:49152
	ds_read_b128 v[184:187], v163 offset:50176
	ds_read_b128 v[188:191], v163 offset:51200
	ds_read_b128 v[192:195], v163 offset:52224
	ds_read_b128 v[196:199], v163 offset:53248
	ds_read_b128 v[204:207], v163 offset:54272
	ds_read_b128 v[208:211], v163 offset:55296
	ds_read_b128 v[212:215], v163 offset:56320
	global_load_lds_dwordx4 v[156:157], off
	s_add_i32 m0, s38, 0x2000
	s_add_u32 s36, s36, 0x40080
	v_lshl_add_u64 v[156:157], v[200:201], 0, s[10:11]
	s_addc_u32 s37, s37, 0
	s_add_i32 s38, s63, s44
	global_load_lds_dwordx4 v[156:157], off
	v_lshl_add_u64 v[156:157], s[36:37], 0, v[144:145]
	s_mov_b32 m0, s38
	s_nop 0
	global_load_lds_dwordx4 v[156:157], off
	v_lshl_add_u64 v[156:157], s[36:37], 0, v[146:147]
	s_add_i32 m0, s38, 0x2000
	s_nop 0
	global_load_lds_dwordx4 v[156:157], off
	v_lshl_add_u64 v[156:157], v[216:217], 0, s[10:11]
	s_mov_b32 m0, s51
	s_nop 0
	global_load_lds_dwordx4 v[156:157], off
	v_lshl_add_u64 v[156:157], v[218:219], 0, s[10:11]
	s_mov_b32 m0, s52
	s_nop 0
	global_load_lds_dwordx4 v[156:157], off
	s_waitcnt vmcnt(8)
	s_waitcnt lgkmcnt(0)
	s_barrier
	s_setprio 1
	s_waitcnt lgkmcnt(0)
	v_mfma_f32_16x16x32_bf16 v[60:63], v[128:131], v[180:183], v[60:63]
	v_mfma_f32_16x16x32_bf16 v[56:59], v[136:139], v[180:183], v[56:59]
	v_mfma_f32_16x16x32_bf16 v[48:51], v[128:131], v[188:191], v[48:51]
	v_mfma_f32_16x16x32_bf16 v[44:47], v[136:139], v[188:191], v[44:47]
	v_mfma_f32_16x16x32_bf16 v[32:35], v[128:131], v[196:199], v[32:35]
	v_mfma_f32_16x16x32_bf16 v[28:31], v[136:139], v[196:199], v[28:31]
	v_mfma_f32_16x16x32_bf16 v[16:19], v[128:131], v[208:211], v[16:19]
	v_mfma_f32_16x16x32_bf16 v[12:15], v[136:139], v[208:211], v[12:15]
	v_mfma_f32_16x16x32_bf16 v[60:63], v[132:135], v[184:187], v[60:63]
	v_mfma_f32_16x16x32_bf16 v[56:59], v[140:143], v[184:187], v[56:59]
	v_mfma_f32_16x16x32_bf16 v[48:51], v[132:135], v[192:195], v[48:51]
	v_mfma_f32_16x16x32_bf16 v[44:47], v[140:143], v[192:195], v[44:47]
	v_mfma_f32_16x16x32_bf16 v[32:35], v[132:135], v[204:207], v[32:35]
	v_mfma_f32_16x16x32_bf16 v[28:31], v[140:143], v[204:207], v[28:31]
	v_mfma_f32_16x16x32_bf16 v[16:19], v[132:135], v[212:215], v[16:19]
	v_mfma_f32_16x16x32_bf16 v[12:15], v[140:143], v[212:215], v[12:15]
	s_setprio 0
	s_setprio 1
	v_mfma_f32_16x16x32_bf16 v[52:55], v[164:167], v[180:183], v[52:55]
	v_mfma_f32_16x16x32_bf16 v[40:43], v[172:175], v[180:183], v[40:43]
	v_mfma_f32_16x16x32_bf16 v[36:39], v[164:167], v[188:191], v[36:39]
	v_mfma_f32_16x16x32_bf16 v[24:27], v[172:175], v[188:191], v[24:27]
	v_mfma_f32_16x16x32_bf16 v[20:23], v[164:167], v[196:199], v[20:23]
	v_mfma_f32_16x16x32_bf16 v[8:11], v[172:175], v[196:199], v[8:11]
	v_mfma_f32_16x16x32_bf16 v[4:7], v[164:167], v[208:211], v[4:7]
	v_mfma_f32_16x16x32_bf16 v[0:3], v[172:175], v[208:211], v[0:3]
	v_mfma_f32_16x16x32_bf16 v[52:55], v[168:171], v[184:187], v[52:55]
	v_mfma_f32_16x16x32_bf16 v[40:43], v[176:179], v[184:187], v[40:43]
	v_mfma_f32_16x16x32_bf16 v[36:39], v[168:171], v[192:195], v[36:39]
	v_mfma_f32_16x16x32_bf16 v[24:27], v[176:179], v[192:195], v[24:27]
	v_mfma_f32_16x16x32_bf16 v[20:23], v[168:171], v[204:207], v[20:23]
	v_mfma_f32_16x16x32_bf16 v[8:11], v[176:179], v[204:207], v[8:11]
	v_mfma_f32_16x16x32_bf16 v[4:7], v[168:171], v[212:215], v[4:7]
	v_mfma_f32_16x16x32_bf16 v[0:3], v[176:179], v[212:215], v[0:3]
	s_setprio 0
	s_barrier
	s_add_i32 s61, s61, 2
	s_add_u32 s59, s59, 0x100
	s_addc_u32 s60, s60, 0
	s_add_u32 s34, s34, 0x100
	s_addc_u32 s35, s35, 0
	s_cmp_gt_u32 s61, 13
	s_cbranch_scc0 .LBB0_579
	s_and_b64 vcc, exec, s[12:13]
	s_cbranch_vccz .LBB0_582
	s_barrier
.LBB0_582:
	v_lshl_add_u32 v170, s30, 8, v158
	v_lshl_or_b32 v168, s56, 8, v160
	s_ashr_i32 s23, s30, 3
	v_ashrrev_i32_e32 v171, 31, v170
	s_mul_hi_i32 s25, s23, 0x3000
	s_mulk_i32 s23, 0x3000
	v_ashrrev_i32_e32 v169, 31, v168
	v_lshlrev_b64 v[130:131], 10, v[170:171]
	s_add_u32 s34, s49, s23
	v_lshl_add_u64 v[130:131], v[130:131], 0, v[168:169]
	s_addc_u32 s35, s50, s25
	v_lshlrev_b64 v[156:157], 2, v[130:131]
	v_lshl_add_u64 v[128:129], v[168:169], 2, s[34:35]
	v_and_b32_e32 v165, 0xffffff00, v170
	v_and_b32_e32 v166, 15, v170
	v_lshl_add_u32 v165, v166, 3, v165
	v_bfe_u32 v166, v170, 6, 1
	v_lshl_add_u32 v165, v166, 2, v165
	v_lshlrev_b32_e32 v165, 12, v165
	v_lshl_add_u32 v156, v168, 2, v165
	global_load_dwordx4 v[140:143], v[128:129], off
	global_load_dwordx4 v[136:139], v[128:129], off offset:64
	global_load_dwordx4 v[132:135], v[128:129], off offset:512
	s_nop 0
	global_load_dwordx4 v[128:131], v[128:129], off offset:576
	s_andn2_b64 vcc, exec, s[4:5]
	s_mov_b64 s[4:5], -1
	s_mov_b64 s[36:37], s[0:1]
	global_load_dwordx4 v[164:167], v156, s[36:37]
	global_load_dwordx4 v[168:171], v156, s[36:37] offset:64
	global_load_dwordx4 v[172:175], v156, s[36:37] offset:512
	global_load_dwordx4 v[176:179], v156, s[36:37] offset:576
	s_add_u32 s36, s0, 0x1000
	s_addc_u32 s37, s1, 0
	global_load_dwordx4 v[180:183], v156, s[36:37]
	global_load_dwordx4 v[184:187], v156, s[36:37] offset:64
	global_load_dwordx4 v[188:191], v156, s[36:37] offset:512
	global_load_dwordx4 v[192:195], v156, s[36:37] offset:576
	s_add_u32 s36, s0, 0x2000
	s_addc_u32 s37, s1, 0
	global_load_dwordx4 v[196:199], v156, s[36:37]
	global_load_dwordx4 v[204:207], v156, s[36:37] offset:64
	global_load_dwordx4 v[208:211], v156, s[36:37] offset:512
	global_load_dwordx4 v[212:215], v156, s[36:37] offset:576
	s_waitcnt vmcnt(8)
;     __device__ __forceinline__ void operator()(const f32x4 (&acc)[2][2][4][2], const pg8::Unit& u, int wr, int wc, int fr, int fq) const {
;     ...
;                 const size_t off = (size_t)(row0 + ai * 128 + m * 16) * DM + col0;
; #pragma unroll
;                 for (int bj = 0; bj < 2; ++bj)
; #pragma unroll
;                     for (int n = 0; n < 2; ++n) {
;                         const f32x4 xv = *(const f32x4*)(xin + off + bj * 128 + n * 16);
;                         *(f32x4*)(out + off + bj * 128 + n * 16) = xv + gv[bj][n] * acc[ai][bj][m][n];
;                     }
	v_pk_fma_f32 v[166:167], v[126:127], v[142:143], v[166:167]
	v_pk_fma_f32 v[164:165], v[124:125], v[140:141], v[164:165]
	v_pk_fma_f32 v[170:171], v[122:123], v[138:139], v[170:171]
	v_pk_fma_f32 v[168:169], v[120:121], v[136:137], v[168:169]
	v_pk_fma_f32 v[174:175], v[118:119], v[134:135], v[174:175]
	v_pk_fma_f32 v[172:173], v[116:117], v[132:133], v[172:173]
	v_pk_fma_f32 v[178:179], v[106:107], v[130:131], v[178:179]
	v_pk_fma_f32 v[176:177], v[104:105], v[128:129], v[176:177]
	s_mov_b64 s[38:39], s[8:9]
	global_store_dwordx4 v156, v[164:167], s[38:39]
	global_store_dwordx4 v156, v[168:171], s[38:39] offset:64
	global_store_dwordx4 v156, v[172:175], s[38:39] offset:512
	global_store_dwordx4 v156, v[176:179], s[38:39] offset:576
	s_add_u32 s36, s0, 0x3000
	s_addc_u32 s37, s1, 0
	global_load_dwordx4 v[164:167], v156, s[36:37]
	global_load_dwordx4 v[168:171], v156, s[36:37] offset:64
	global_load_dwordx4 v[172:175], v156, s[36:37] offset:512
	global_load_dwordx4 v[176:179], v156, s[36:37] offset:576
	s_waitcnt vmcnt(12)
	v_pk_fma_f32 v[182:183], v[114:115], v[142:143], v[182:183]
	v_pk_fma_f32 v[180:181], v[112:113], v[140:141], v[180:181]
	v_pk_fma_f32 v[186:187], v[110:111], v[138:139], v[186:187]
	v_pk_fma_f32 v[184:185], v[108:109], v[136:137], v[184:185]
	v_pk_fma_f32 v[190:191], v[102:103], v[134:135], v[190:191]
	v_pk_fma_f32 v[188:189], v[100:101], v[132:133], v[188:189]
	v_pk_fma_f32 v[194:195], v[90:91], v[130:131], v[194:195]
	v_pk_fma_f32 v[192:193], v[88:89], v[128:129], v[192:193]
	s_add_u32 s38, s8, 0x1000
	s_addc_u32 s39, s9, 0
	global_store_dwordx4 v156, v[180:183], s[38:39]
	global_store_dwordx4 v156, v[184:187], s[38:39] offset:64
	global_store_dwordx4 v156, v[188:191], s[38:39] offset:512
	global_store_dwordx4 v156, v[192:195], s[38:39] offset:576
	s_add_u32 s36, s0, 0x80000
	s_addc_u32 s37, s1, 0
	global_load_dwordx4 v[180:183], v156, s[36:37]
	global_load_dwordx4 v[184:187], v156, s[36:37] offset:64
	global_load_dwordx4 v[188:191], v156, s[36:37] offset:512
	global_load_dwordx4 v[192:195], v156, s[36:37] offset:576
	s_waitcnt vmcnt(16)
	v_pk_fma_f32 v[198:199], v[98:99], v[142:143], v[198:199]
	v_pk_fma_f32 v[196:197], v[96:97], v[140:141], v[196:197]
	v_pk_fma_f32 v[206:207], v[94:95], v[138:139], v[206:207]
	v_pk_fma_f32 v[204:205], v[92:93], v[136:137], v[204:205]
	v_pk_fma_f32 v[210:211], v[86:87], v[134:135], v[210:211]
	v_pk_fma_f32 v[208:209], v[84:85], v[132:133], v[208:209]
	v_pk_fma_f32 v[214:215], v[74:75], v[130:131], v[214:215]
	v_pk_fma_f32 v[212:213], v[72:73], v[128:129], v[212:213]
	s_add_u32 s38, s8, 0x2000
	s_addc_u32 s39, s9, 0
	global_store_dwordx4 v156, v[196:199], s[38:39]
	global_store_dwordx4 v156, v[204:207], s[38:39] offset:64
	global_store_dwordx4 v156, v[208:211], s[38:39] offset:512
	global_store_dwordx4 v156, v[212:215], s[38:39] offset:576
	s_add_u32 s36, s0, 0x81000
	s_addc_u32 s37, s1, 0
	global_load_dwordx4 v[196:199], v156, s[36:37]
	global_load_dwordx4 v[204:207], v156, s[36:37] offset:64
	global_load_dwordx4 v[208:211], v156, s[36:37] offset:512
	global_load_dwordx4 v[212:215], v156, s[36:37] offset:576
	s_waitcnt vmcnt(16)
	v_pk_fma_f32 v[166:167], v[82:83], v[142:143], v[166:167]
	v_pk_fma_f32 v[164:165], v[80:81], v[140:141], v[164:165]
	v_pk_fma_f32 v[170:171], v[78:79], v[138:139], v[170:171]
	v_pk_fma_f32 v[168:169], v[76:77], v[136:137], v[168:169]
	v_pk_fma_f32 v[174:175], v[70:71], v[134:135], v[174:175]
	v_pk_fma_f32 v[172:173], v[68:69], v[132:133], v[172:173]
	v_pk_fma_f32 v[178:179], v[66:67], v[130:131], v[178:179]
	v_pk_fma_f32 v[176:177], v[64:65], v[128:129], v[176:177]
	s_add_u32 s38, s8, 0x3000
	s_addc_u32 s39, s9, 0
	global_store_dwordx4 v156, v[164:167], s[38:39]
	global_store_dwordx4 v156, v[168:171], s[38:39] offset:64
	global_store_dwordx4 v156, v[172:175], s[38:39] offset:512
	global_store_dwordx4 v156, v[176:179], s[38:39] offset:576
	s_add_u32 s36, s0, 0x82000
	s_addc_u32 s37, s1, 0
	global_load_dwordx4 v[164:167], v156, s[36:37]
	global_load_dwordx4 v[168:171], v156, s[36:37] offset:64
	global_load_dwordx4 v[172:175], v156, s[36:37] offset:512
	global_load_dwordx4 v[176:179], v156, s[36:37] offset:576
	s_waitcnt vmcnt(16)
;     __device__ __forceinline__ void operator()(const f32x4 (&acc)[2][2][4][2], const pg8::Unit& u, int wr, int wc, int fr, int fq) const {
;     ...
;                 const size_t off = (size_t)(row0 + ai * 128 + m * 16) * DM + col0;
; #pragma unroll
;                 for (int bj = 0; bj < 2; ++bj)
; #pragma unroll
;                     for (int n = 0; n < 2; ++n) {
;                         const f32x4 xv = *(const f32x4*)(xin + off + bj * 128 + n * 16);
;                         *(f32x4*)(out + off + bj * 128 + n * 16) = xv + gv[bj][n] * acc[ai][bj][m][n];
;                     }
	v_pk_fma_f32 v[182:183], v[62:63], v[142:143], v[182:183]
	v_pk_fma_f32 v[180:181], v[60:61], v[140:141], v[180:181]
	v_pk_fma_f32 v[186:187], v[58:59], v[138:139], v[186:187]
	v_pk_fma_f32 v[184:185], v[56:57], v[136:137], v[184:185]
	v_pk_fma_f32 v[190:191], v[54:55], v[134:135], v[190:191]
	v_pk_fma_f32 v[188:189], v[52:53], v[132:133], v[188:189]
	v_pk_fma_f32 v[194:195], v[42:43], v[130:131], v[194:195]
	v_pk_fma_f32 v[192:193], v[40:41], v[128:129], v[192:193]
	s_add_u32 s38, s8, 0x80000
	s_addc_u32 s39, s9, 0
	global_store_dwordx4 v156, v[180:183], s[38:39]
	global_store_dwordx4 v156, v[184:187], s[38:39] offset:64
	global_store_dwordx4 v156, v[188:191], s[38:39] offset:512
	global_store_dwordx4 v156, v[192:195], s[38:39] offset:576
	s_add_u32 s36, s0, 0x83000
	s_addc_u32 s37, s1, 0
	global_load_dwordx4 v[180:183], v156, s[36:37]
	global_load_dwordx4 v[184:187], v156, s[36:37] offset:64
	global_load_dwordx4 v[188:191], v156, s[36:37] offset:512
	global_load_dwordx4 v[192:195], v156, s[36:37] offset:576
	s_waitcnt vmcnt(16)
	v_pk_fma_f32 v[198:199], v[50:51], v[142:143], v[198:199]
	v_pk_fma_f32 v[196:197], v[48:49], v[140:141], v[196:197]
	v_pk_fma_f32 v[206:207], v[46:47], v[138:139], v[206:207]
	v_pk_fma_f32 v[204:205], v[44:45], v[136:137], v[204:205]
	v_pk_fma_f32 v[210:211], v[38:39], v[134:135], v[210:211]
	v_pk_fma_f32 v[208:209], v[36:37], v[132:133], v[208:209]
	v_pk_fma_f32 v[214:215], v[26:27], v[130:131], v[214:215]
	v_pk_fma_f32 v[212:213], v[24:25], v[128:129], v[212:213]
	s_add_u32 s38, s8, 0x81000
	s_addc_u32 s39, s9, 0
	global_store_dwordx4 v156, v[196:199], s[38:39]
	global_store_dwordx4 v156, v[204:207], s[38:39] offset:64
	global_store_dwordx4 v156, v[208:211], s[38:39] offset:512
	global_store_dwordx4 v156, v[212:215], s[38:39] offset:576
	s_waitcnt vmcnt(12)
	v_pk_fma_f32 v[166:167], v[34:35], v[142:143], v[166:167]
	v_pk_fma_f32 v[164:165], v[32:33], v[140:141], v[164:165]
	v_pk_fma_f32 v[170:171], v[30:31], v[138:139], v[170:171]
	v_pk_fma_f32 v[168:169], v[28:29], v[136:137], v[168:169]
	v_pk_fma_f32 v[174:175], v[22:23], v[134:135], v[174:175]
	v_pk_fma_f32 v[172:173], v[20:21], v[132:133], v[172:173]
	v_pk_fma_f32 v[178:179], v[10:11], v[130:131], v[178:179]
	v_pk_fma_f32 v[176:177], v[8:9], v[128:129], v[176:177]
	s_add_u32 s38, s8, 0x82000
	s_addc_u32 s39, s9, 0
	global_store_dwordx4 v156, v[164:167], s[38:39]
	global_store_dwordx4 v156, v[168:171], s[38:39] offset:64
	global_store_dwordx4 v156, v[172:175], s[38:39] offset:512
	global_store_dwordx4 v156, v[176:179], s[38:39] offset:576
	s_waitcnt vmcnt(8)
	v_pk_fma_f32 v[182:183], v[18:19], v[142:143], v[182:183]
	v_pk_fma_f32 v[180:181], v[16:17], v[140:141], v[180:181]
	v_pk_fma_f32 v[186:187], v[14:15], v[138:139], v[186:187]
	v_pk_fma_f32 v[184:185], v[12:13], v[136:137], v[184:185]
	v_pk_fma_f32 v[190:191], v[6:7], v[134:135], v[190:191]
	v_pk_fma_f32 v[188:189], v[4:5], v[132:133], v[188:189]
	v_pk_fma_f32 v[194:195], v[2:3], v[130:131], v[194:195]
	v_pk_fma_f32 v[192:193], v[0:1], v[128:129], v[192:193]
	s_add_u32 s38, s8, 0x83000
	s_addc_u32 s39, s9, 0
	global_store_dwordx4 v156, v[180:183], s[38:39]
	global_store_dwordx4 v156, v[184:187], s[38:39] offset:64
	global_store_dwordx4 v156, v[188:191], s[38:39] offset:512
	global_store_dwordx4 v156, v[192:195], s[38:39] offset:576
	s_cbranch_vccnz .LBB0_571
	s_andn2_b64 vcc, exec, s[6:7]
	s_cbranch_vccnz .LBB0_570
	s_barrier
	s_branch .LBB0_570

; #define PG8_STAGE(bufoff, gbase, voff) do { _Pragma("unroll") for (int _i = 0; _i < 2; ++_i) \
;         __builtin_amdgcn_global_load_lds((const unsigned*)((const char*)(gbase) + (voff)[_i]), (PG8_LAS unsigned*)(lds + (bufoff) + ldsw + _i * 8192), 16, 0, 0); } while (0)
; #define PG8_WAIT_V(n) asm volatile("s_waitcnt vmcnt(" #n ")" ::: "memory")
; #define PG8_BAR __builtin_amdgcn_s_barrier()
; template <class Epi, class Sched, bool ALIGN_EPI = false, bool SP2 = false>
; __device__ __forceinline__ void gemm_phase(PG8_LAS unsigned char* lds, const Gemm g, const Sched& S, const Epi& E) {
;     ...
;     unsigned voffA[2], voffB[2];
; #pragma unroll
;     for (int i = 0; i < 2; ++i) { int R, C; stage_rc(tid * 16 + i * 8192, R, C); const int Rb = Epi::PERM ? ((R & ~31) + perm32(R & 31)) : R;
;         voffA[i] = (unsigned)(R * K + C) * 2u; voffB[i] = (unsigned)(Rb * K + C) * 2u; }
;     ...
;         PG8_STAGE(PG8_SB(0, 0), cB, voffB); PG8_STAGE(PG8_SB(0, 1), cB + hstep, voffB); PG8_STAGE(PG8_SA(0, 0), cA, voffA); PG8_STAGE(PG8_SA(0, 1), cA + hstep, voffA);
;         if (wr == 1) PG8_BAR;
;         PG8_WAIT_V(2); PG8_BAR;
;         PG8_STAGE(PG8_SB(1, 0), cB + kstep, voffB); PG8_STAGE(PG8_SA(1, 0), cA + kstep, voffA); PG8_STAGE(PG8_SB(1, 1), cB + hstep + kstep, voffB);
;         PG8_WAIT_V(6); PG8_BAR;
.LBB0_1092:
	v_ashrrev_i32_e32 v1, 31, v8
	v_lshrrev_b32_e32 v1, 26, v1
	v_add_u32_e32 v1, v8, v1
	v_ashrrev_i32_e32 v9, 6, v1
	v_bfe_i32 v1, v8, 27, 1
	v_lshlrev_b32_e32 v0, 4, v8
	v_lshrrev_b32_e32 v1, 22, v1
	v_add_u32_e32 v1, v0, v1
	v_and_b32_e32 v1, 0xfffffc00, v1
	v_sub_u32_e32 v1, v0, v1
	v_lshrrev_b32_e32 v2, 4, v1
	v_bitop3_b32 v1, v2, v1, 32 bitop3:0x6c
	v_ashrrev_i32_e32 v3, 31, v1
	v_lshrrev_b32_e32 v3, 26, v3
	s_waitcnt lgkmcnt(0)
	s_add_u32 s38, s6, 0x2000000
	v_add_u32_e32 v3, v1, v3
	s_addc_u32 s39, s7, 0
	v_ashrrev_i32_e32 v10, 6, v3
	v_and_b32_e32 v3, 0xc0, v3
	s_add_u32 s40, s6, 0x1800000
	v_sub_u32_e32 v1, v1, v3
	v_mov_b32_e32 v3, 1
	s_addc_u32 s41, s7, 0
	v_lshlrev_b32_e32 v2, 3, v9
	v_lshlrev_b32_e32 v4, 5, v9
	v_ashrrev_i16_sdwa v1, v3, sext(v1) dst_sel:DWORD dst_unused:UNUSED_PAD src0_sel:DWORD src1_sel:BYTE_0
	s_add_i32 s0, s12, s0
	v_and_b32_e32 v2, 0x1ffff0, v2
	v_and_b32_e32 v4, 32, v4
	v_bfe_i32 v11, v1, 0, 16
	s_ashr_i32 s8, s0, 31
	v_add_u32_e32 v1, v4, v11
	v_add_lshl_u32 v2, v10, v2, 11
	v_add_u32_e32 v0, 0x2000, v0
	s_lshr_b32 s8, s8, 27
	v_lshl_add_u32 v144, v1, 1, v2
	v_ashrrev_i32_e32 v1, 31, v0
	s_add_i32 s8, s0, s8
	v_lshrrev_b32_e32 v1, 22, v1
	s_ashr_i32 s9, s8, 5
	s_and_b32 s8, s8, 0xffe0
	v_add_u32_e32 v1, v0, v1
	s_sub_i32 s8, s0, s8
	v_ashrrev_i32_e32 v12, 10, v1
	s_bfe_i32 s0, s8, 0x80000
	v_mul_i32_i24_e32 v1, 0x400, v12
	s_bfe_u32 s0, s0, 0x3000c
	v_sub_u32_e32 v0, v0, v1
	s_add_i32 s12, s8, s0
	v_lshrrev_b32_e32 v1, 4, v0
	s_bfe_i32 s0, s12, 0x80000
	s_and_b32 s12, s12, 0xf8
	v_bitop3_b32 v0, v1, v0, 32 bitop3:0x6c
	s_sub_i32 s8, s8, s12
	v_ashrrev_i32_e32 v2, 31, v0
	s_lshl_b32 s9, s9, 3
	s_sext_i32_i16 s0, s0
	s_sext_i32_i8 s8, s8
	s_ashr_i32 s1, s10, 8
	v_lshrrev_b32_e32 v2, 26, v2
	s_lshr_b32 s0, s0, 3
	s_add_i32 s28, s9, s8
	v_add_u32_e32 v2, v0, v2
	s_ashr_i32 s11, s10, 6
	s_ashr_i32 s29, s28, 31
	s_bfe_i64 s[12:13], s[0:1], 0x100000
	v_ashrrev_i32_e32 v13, 6, v2
	v_and_b32_e32 v2, 0xc0, v2
	s_lshl_b32 s42, s11, 10
	s_lshl_b64 s[8:9], s[28:29], 19
	s_lshl_b64 s[12:13], s[12:13], 19
	v_sub_u32_e32 v0, v0, v2
	s_add_u32 s30, s40, s12
	v_lshlrev_b32_e32 v1, 3, v12
	v_lshlrev_b32_e32 v4, 5, v12
	v_ashrrev_i16_sdwa v0, v3, sext(v0) dst_sel:DWORD dst_unused:UNUSED_PAD src0_sel:DWORD src1_sel:BYTE_0
	s_addc_u32 s31, s41, s13
	s_add_i32 s29, s42, 0
	v_and_b32_e32 v1, 0x1ffff0, v1
	v_and_b32_e32 v4, 32, v4
	v_bfe_i32 v14, v0, 0, 16
	s_add_i32 m0, s29, 0x10000
	v_add_u32_e32 v0, v4, v14
	v_add_lshl_u32 v1, v13, v1, 11
	global_load_lds_dwordx4 v144, s[30:31]
	s_add_i32 m0, s29, 0x12000
	v_lshl_add_u32 v146, v0, 1, v1
	v_lshrrev_b32_e32 v222, 11, v144
	v_and_b32_e32 v223, 15, v222
	v_lshlrev_b32_e32 v223, 3, v223
	v_bfe_u32 v150, v222, 6, 1
	v_lshl_or_b32 v223, v150, 2, v223
	v_bfe_u32 v150, v222, 4, 2
	v_or_b32_e32 v223, v223, v150
	v_and_b32_e32 v150, 0x7ff, v144
	v_lshl_or_b32 v150, v223, 11, v150
	v_lshrrev_b32_e32 v222, 11, v146
	v_and_b32_e32 v223, 15, v222
	v_lshlrev_b32_e32 v223, 3, v223
	v_bfe_u32 v148, v222, 6, 1
	v_lshl_or_b32 v223, v148, 2, v223
	v_bfe_u32 v148, v222, 4, 2
	v_or_b32_e32 v223, v223, v148
	v_and_b32_e32 v148, 0x7ff, v146
	v_lshl_or_b32 v148, v223, 11, v148
	v_mov_b32_e32 v149, 0
	v_mov_b32_e32 v151, 0
	s_add_u32 s12, s30, 0x40000
	global_load_lds_dwordx4 v146, s[30:31]
	s_addc_u32 s13, s31, 0
	s_add_i32 m0, s29, 0x14000
	v_mov_b32_e32 v145, 0
	global_load_lds_dwordx4 v144, s[12:13]
	s_add_i32 m0, s29, 0x16000
	s_add_u32 s34, s38, s8
	s_addc_u32 s35, s39, s9
	s_add_i32 s43, s29, 0x2000
	global_load_lds_dwordx4 v146, s[12:13]
	s_mov_b32 m0, s29
	s_add_u32 s8, s34, 0x40000
	global_load_lds_dwordx4 v150, s[34:35]
	s_mov_b32 m0, s43
	s_addc_u32 s9, s35, 0
	s_add_i32 s44, s29, 0x4000
	global_load_lds_dwordx4 v148, s[34:35]
	s_mov_b32 m0, s44
	s_add_i32 s45, s29, 0x6000
	global_load_lds_dwordx4 v150, s[8:9]
	s_mov_b32 m0, s45
	v_mov_b32_e32 v147, v145
	global_load_lds_dwordx4 v148, s[8:9]
	s_cmp_eq_u32 s1, 1
	s_mov_b32 s46, 0
	v_lshl_add_u64 v[6:7], s[30:31], 0, v[144:145]
	v_lshl_add_u64 v[4:5], s[30:31], 0, v[146:147]
	v_lshl_add_u64 v[0:1], s[34:35], 0, v[150:151]
	s_cselect_b64 s[8:9], -1, 0
	s_cmp_lg_u32 s1, 1
	v_lshl_add_u64 v[2:3], s[34:35], 0, v[148:149]
	s_cbranch_scc1 .LBB0_1094
	s_barrier
.LBB0_1094:
	s_add_u32 s47, s6, 0x162000
	s_addc_u32 s48, s7, 0
	s_lshl_b32 s6, s11, 5
	s_and_b32 s15, s6, 0x60
	s_mov_b64 s[6:7], 0x80
	s_add_i32 m0, s29, 0x18000
	v_lshl_add_u64 v[6:7], v[6:7], 0, s[6:7]
	s_lshl_b32 s14, s1, 13
	s_lshl_b32 s11, s15, 7
	s_waitcnt vmcnt(2)
	s_barrier
	global_load_lds_dwordx4 v[6:7], off
	v_lshl_add_u64 v[4:5], v[4:5], 0, s[6:7]
	s_add_i32 m0, s29, 0x1a000
	s_add_i32 s49, s29, 0x8000
	s_add_i32 s50, s29, 0xa000
	global_load_lds_dwordx4 v[4:5], off
	v_lshl_add_u64 v[0:1], v[0:1], 0, s[6:7]
	s_mov_b32 m0, s49
	s_add_u32 s12, s30, 0x40080
	global_load_lds_dwordx4 v[0:1], off
	v_lshl_add_u64 v[0:1], v[2:3], 0, s[6:7]
	s_mov_b32 m0, s50
	s_addc_u32 s13, s31, 0
	global_load_lds_dwordx4 v[0:1], off
	s_add_i32 m0, s29, 0x1c000
	v_lshl_add_u64 v[0:1], s[12:13], 0, v[144:145]
	global_load_lds_dwordx4 v[0:1], off
	v_lshl_add_u64 v[0:1], s[12:13], 0, v[146:147]
	s_add_i32 m0, s29, 0x1e000
	s_cmpk_lt_u32 s10, 0x100
	global_load_lds_dwordx4 v[0:1], off
	v_bfe_u32 v1, v8, 4, 2
	v_and_b32_e32 v0, 15, v8
	v_lshlrev_b32_e32 v2, 4, v1
	v_lshl_or_b32 v158, s1, 6, v0
	v_lshl_or_b32 v0, v0, 6, v2
	v_lshlrev_b32_e32 v2, 2, v8
	v_and_b32_e32 v2, 32, v2
	v_bitop3_b32 v3, v0, s14, v2 bitop3:0xde
	v_bitop3_b32 v159, v0, s11, v2 bitop3:0xde
	v_lshlrev_b32_e32 v0, 14, v12
	v_and_b32_e32 v0, 0xffff8000, v0
	v_lshl_or_b32 v160, v1, 2, s15
	v_lshl_add_u32 v0, v13, 11, v0
	v_and_b32_e32 v1, 1, v12
	v_lshl_or_b32 v0, v1, 6, v0
	s_nop 0
	v_lshlrev_b32_e32 v0, 14, v9
	v_and_b32_e32 v0, 0xffff8000, v0
	s_waitcnt vmcnt(6)
	v_lshl_add_u32 v0, v10, 11, v0
	v_and_b32_e32 v1, 1, v9
	s_cselect_b64 s[10:11], -1, 0
	v_lshl_or_b32 v0, v1, 6, v0
	s_add_i32 s52, 0, 0x10000
	s_add_i32 s53, 0, 0x14000
	s_sext_i32_i8 s58, s0
	s_ashr_i32 s51, s33, 31
	v_mov_b32_e32 v149, v145
	s_nop 0
	v_mov_b32_e32 v151, v145
	v_mov_b64_e32 v[152:153], 0x400
	v_mov_b64_e32 v[154:155], 0x3ff
	v_add_u32_e32 v161, s52, v159
	v_add_u32_e32 v162, s53, v159
	v_add_u32_e32 v163, 0, v3
	s_mov_b64 s[12:13], 0x80000
	s_mov_b32 s54, 0x80000
	s_mov_b64 s[14:15], 0x90000
	s_mov_b32 s55, 0x90000
	s_mov_b64 s[16:17], 0xa0000
	s_mov_b32 s56, 0xa0000
	s_mov_b64 s[18:19], 0xb0000
	s_mov_b32 s57, 0xb0000
	s_barrier
	s_branch .LBB0_1097

; #define PG8_STAGE(bufoff, gbase, voff) do { _Pragma("unroll") for (int _i = 0; _i < 2; ++_i) \
;         __builtin_amdgcn_global_load_lds((const unsigned*)((const char*)(gbase) + (voff)[_i]), (PG8_LAS unsigned*)(lds + (bufoff) + ldsw + _i * 8192), 16, 0, 0); } while (0)
; #define PG8_LDA(dst, b, h) do { _Pragma("unroll") for (int m = 0; m < 4; ++m) _Pragma("unroll") for (int k = 0; k < 2; ++k) dst[m][k] = *(const PG8_LAS bf16x8*)(lds + PG8_SA(b, h) + aoff + m * 2048 + k * 1024); } while (0)
; #define PG8_LDB(dst, b, h) do { _Pragma("unroll") for (int n = 0; n < 2; ++n) _Pragma("unroll") for (int k = 0; k < 2; ++k) dst[n][k] = *(const PG8_LAS bf16x8*)(lds + PG8_SB(b, h) + boff + n * 2048 + k * 1024); } while (0)
; #define PG8_MMA(ai, bj, At, Bt) do { __builtin_amdgcn_s_setprio(1); _Pragma("unroll") for (int m = 0; m < 4; ++m) _Pragma("unroll") for (int n = 0; n < 2; ++n) _Pragma("unroll") for (int k = 0; k < 2; ++k) \
;         acc[ai][bj][m][n] = __builtin_amdgcn_mfma_f32_16x16x32_bf16(Bt[n][k], At[m][k], acc[ai][bj][m][n], 0, 0, 0); __builtin_amdgcn_s_setprio(0); } while (0)
; #define PG8_WAIT_V(n) asm volatile("s_waitcnt vmcnt(" #n ")" ::: "memory")
; #define PG8_WAIT_L(n) asm volatile("s_waitcnt lgkmcnt(" #n ")" ::: "memory")
; #define PG8_BAR __builtin_amdgcn_s_barrier()
; #define PG8_SCHED __builtin_amdgcn_sched_barrier(0)
; template <class Epi, class Sched, bool ALIGN_EPI = false, bool SP2 = false>
; __device__ __forceinline__ void gemm_phase(PG8_LAS unsigned char* lds, const Gemm g, const Sched& S, const Epi& E) {
;     ...
;             PG8_LDB(B0, 0, 0); PG8_LDB(B1, 0, 1); PG8_SCHED; PG8_LDA(At, 0, 0); PG8_STAGE(PG8_SA(1, 1), a1 + hstep, voffA);
;             PG8_WAIT_V(8); PG8_WAIT_L(0); PG8_BAR; PG8_MMA(0, 0, At, B0); PG8_MMA(0, 1, At, B1); PG8_BAR; PG8_SCHED;
;             PG8_LDA(At, 0, 1); PG8_STAGE(PG8_SB(0, 0), b2, voffB); PG8_STAGE(PG8_SB(0, 1), b2 + hstep, voffB); PG8_STAGE(PG8_SA(0, 0), a2, voffA);
;             PG8_WAIT_V(8); PG8_WAIT_L(0); PG8_BAR; PG8_MMA(1, 0, At, B0); PG8_MMA(1, 1, At, B1); PG8_BAR; PG8_SCHED;
.LBB0_1104:
	ds_read_b128 v[128:131], v161
	ds_read_b128 v[132:135], v161 offset:1024
	ds_read_b128 v[136:139], v161 offset:2048
	ds_read_b128 v[140:143], v161 offset:3072
	ds_read_b128 v[164:167], v162
	ds_read_b128 v[168:171], v162 offset:1024
	ds_read_b128 v[172:175], v162 offset:2048
	ds_read_b128 v[176:179], v162 offset:3072
	s_add_u32 s34, s30, 0xfffc0080
	s_addc_u32 s35, s31, -1
	s_cmp_eq_u32 s63, 12
	s_cselect_b32 s37, s23, s35
	s_cselect_b32 s36, s59, s34
	s_cselect_b32 s35, s21, s62
	s_cselect_b32 s34, s60, s61
	v_lshl_add_u64 v[156:157], s[30:31], 0, v[150:151]
	s_add_i32 m0, s29, 0xc000
	ds_read_b128 v[180:183], v163
	ds_read_b128 v[184:187], v163 offset:1024
	ds_read_b128 v[188:191], v163 offset:2048
	ds_read_b128 v[192:195], v163 offset:3072
	ds_read_b128 v[196:199], v163 offset:4096
	ds_read_b128 v[204:207], v163 offset:5120
	ds_read_b128 v[208:211], v163 offset:6144
	ds_read_b128 v[212:215], v163 offset:7168
	global_load_lds_dwordx4 v[156:157], off
	v_lshl_add_u64 v[156:157], s[30:31], 0, v[148:149]
	s_add_i32 m0, s29, 0xe000
	s_nop 0
	global_load_lds_dwordx4 v[156:157], off
	s_waitcnt vmcnt(8)
	s_waitcnt lgkmcnt(0)
	s_barrier
	s_setprio 1
	s_waitcnt lgkmcnt(0)
	v_mfma_f32_16x16x32_bf16 v[124:127], v[128:131], v[180:183], v[124:127]
	v_mfma_f32_16x16x32_bf16 v[120:123], v[136:139], v[180:183], v[120:123]
	v_mfma_f32_16x16x32_bf16 v[116:119], v[128:131], v[188:191], v[116:119]
	v_mfma_f32_16x16x32_bf16 v[112:115], v[136:139], v[188:191], v[112:115]
	v_mfma_f32_16x16x32_bf16 v[108:111], v[128:131], v[196:199], v[108:111]
	v_mfma_f32_16x16x32_bf16 v[100:103], v[136:139], v[196:199], v[100:103]
	v_mfma_f32_16x16x32_bf16 v[92:95], v[128:131], v[208:211], v[92:95]
	v_mfma_f32_16x16x32_bf16 v[80:83], v[136:139], v[208:211], v[80:83]
	v_mfma_f32_16x16x32_bf16 v[124:127], v[132:135], v[184:187], v[124:127]
	v_mfma_f32_16x16x32_bf16 v[120:123], v[140:143], v[184:187], v[120:123]
	v_mfma_f32_16x16x32_bf16 v[116:119], v[132:135], v[192:195], v[116:119]
	v_mfma_f32_16x16x32_bf16 v[112:115], v[140:143], v[192:195], v[112:115]
	v_mfma_f32_16x16x32_bf16 v[108:111], v[132:135], v[204:207], v[108:111]
	v_mfma_f32_16x16x32_bf16 v[100:103], v[140:143], v[204:207], v[100:103]
	v_mfma_f32_16x16x32_bf16 v[92:95], v[132:135], v[212:215], v[92:95]
	v_mfma_f32_16x16x32_bf16 v[80:83], v[140:143], v[212:215], v[80:83]
	s_setprio 0
	s_setprio 1
	v_mfma_f32_16x16x32_bf16 v[104:107], v[164:167], v[180:183], v[104:107]
	v_mfma_f32_16x16x32_bf16 v[96:99], v[172:175], v[180:183], v[96:99]
	v_mfma_f32_16x16x32_bf16 v[88:91], v[164:167], v[188:191], v[88:91]
	v_mfma_f32_16x16x32_bf16 v[84:87], v[172:175], v[188:191], v[84:87]
	v_mfma_f32_16x16x32_bf16 v[76:79], v[164:167], v[196:199], v[76:79]
	v_mfma_f32_16x16x32_bf16 v[72:75], v[172:175], v[196:199], v[72:75]
	v_mfma_f32_16x16x32_bf16 v[68:71], v[164:167], v[208:211], v[68:71]
	v_mfma_f32_16x16x32_bf16 v[64:67], v[172:175], v[208:211], v[64:67]
	v_mfma_f32_16x16x32_bf16 v[104:107], v[168:171], v[184:187], v[104:107]
	v_mfma_f32_16x16x32_bf16 v[96:99], v[176:179], v[184:187], v[96:99]
	v_mfma_f32_16x16x32_bf16 v[88:91], v[168:171], v[192:195], v[88:91]
	v_mfma_f32_16x16x32_bf16 v[84:87], v[176:179], v[192:195], v[84:87]
	v_mfma_f32_16x16x32_bf16 v[76:79], v[168:171], v[204:207], v[76:79]
	v_mfma_f32_16x16x32_bf16 v[72:75], v[176:179], v[204:207], v[72:75]
	v_mfma_f32_16x16x32_bf16 v[68:71], v[168:171], v[212:215], v[68:71]
	v_mfma_f32_16x16x32_bf16 v[64:67], v[176:179], v[212:215], v[64:67]
	s_setprio 0
	s_barrier
	s_add_i32 s64, s52, s42
	v_lshl_add_u64 v[156:157], s[34:35], 0, v[144:145]
	s_mov_b32 m0, s64
	ds_read_b128 v[180:183], v163 offset:16384
	ds_read_b128 v[184:187], v163 offset:17408
	ds_read_b128 v[188:191], v163 offset:18432
	ds_read_b128 v[192:195], v163 offset:19456
	ds_read_b128 v[196:199], v163 offset:20480
	ds_read_b128 v[204:207], v163 offset:21504
	ds_read_b128 v[208:211], v163 offset:22528
	ds_read_b128 v[212:215], v163 offset:23552
	global_load_lds_dwordx4 v[156:157], off
	s_add_i32 m0, s64, 0x2000
	s_add_u32 s64, s34, 0x40000
	v_lshl_add_u64 v[200:201], s[34:35], 0, v[146:147]
	s_addc_u32 s65, s35, 0
	s_add_i32 s66, s53, s42
	global_load_lds_dwordx4 v[200:201], off
	v_lshl_add_u64 v[216:217], s[64:65], 0, v[144:145]
	s_mov_b32 m0, s66
	v_lshl_add_u64 v[218:219], s[36:37], 0, v[148:149]
	global_load_lds_dwordx4 v[216:217], off
	v_lshl_add_u64 v[216:217], s[64:65], 0, v[146:147]
	s_add_i32 m0, s66, 0x2000
	s_nop 0
	global_load_lds_dwordx4 v[216:217], off
	v_lshl_add_u64 v[216:217], s[36:37], 0, v[150:151]
	s_mov_b32 m0, s29
	s_nop 0
	global_load_lds_dwordx4 v[216:217], off
	s_mov_b32 m0, s43
	s_nop 0
	global_load_lds_dwordx4 v[218:219], off
	s_waitcnt vmcnt(8)
	s_waitcnt lgkmcnt(0)
	s_barrier
; #define PG8_STAGE(bufoff, gbase, voff) do { _Pragma("unroll") for (int _i = 0; _i < 2; ++_i) \
;         __builtin_amdgcn_global_load_lds((const unsigned*)((const char*)(gbase) + (voff)[_i]), (PG8_LAS unsigned*)(lds + (bufoff) + ldsw + _i * 8192), 16, 0, 0); } while (0)
; #define PG8_LDA(dst, b, h) do { _Pragma("unroll") for (int m = 0; m < 4; ++m) _Pragma("unroll") for (int k = 0; k < 2; ++k) dst[m][k] = *(const PG8_LAS bf16x8*)(lds + PG8_SA(b, h) + aoff + m * 2048 + k * 1024); } while (0)
; #define PG8_LDB(dst, b, h) do { _Pragma("unroll") for (int n = 0; n < 2; ++n) _Pragma("unroll") for (int k = 0; k < 2; ++k) dst[n][k] = *(const PG8_LAS bf16x8*)(lds + PG8_SB(b, h) + boff + n * 2048 + k * 1024); } while (0)
; #define PG8_MMA(ai, bj, At, Bt) do { __builtin_amdgcn_s_setprio(1); _Pragma("unroll") for (int m = 0; m < 4; ++m) _Pragma("unroll") for (int n = 0; n < 2; ++n) _Pragma("unroll") for (int k = 0; k < 2; ++k) \
;         acc[ai][bj][m][n] = __builtin_amdgcn_mfma_f32_16x16x32_bf16(Bt[n][k], At[m][k], acc[ai][bj][m][n], 0, 0, 0); __builtin_amdgcn_s_setprio(0); } while (0)
; #define PG8_WAIT_V(n) asm volatile("s_waitcnt vmcnt(" #n ")" ::: "memory")
; #define PG8_WAIT_L(n) asm volatile("s_waitcnt lgkmcnt(" #n ")" ::: "memory")
; #define PG8_BAR __builtin_amdgcn_s_barrier()
; #define PG8_SCHED __builtin_amdgcn_sched_barrier(0)
; template <class Epi, class Sched, bool ALIGN_EPI = false, bool SP2 = false>
; __device__ __forceinline__ void gemm_phase(PG8_LAS unsigned char* lds, const Gemm g, const Sched& S, const Epi& E) {
;     ...
;             PG8_WAIT_V(8); PG8_WAIT_L(0); PG8_BAR; PG8_MMA(1, 0, At, B0); PG8_MMA(1, 1, At, B1); PG8_BAR; PG8_SCHED;
;             PG8_LDB(B0, 1, 0); PG8_LDB(B1, 1, 1); PG8_SCHED; PG8_LDA(At, 1, 0); PG8_STAGE(PG8_SA(0, 1), a2 + hstep, voffA);
;             PG8_WAIT_V(8); PG8_WAIT_L(0); PG8_BAR; PG8_MMA(0, 0, At, B0); PG8_MMA(0, 1, At, B1); PG8_BAR; PG8_SCHED;
	s_setprio 1
	s_waitcnt lgkmcnt(0)
	v_mfma_f32_16x16x32_bf16 v[60:63], v[128:131], v[180:183], v[60:63]
	v_mfma_f32_16x16x32_bf16 v[56:59], v[136:139], v[180:183], v[56:59]
	v_mfma_f32_16x16x32_bf16 v[52:55], v[128:131], v[188:191], v[52:55]
	v_mfma_f32_16x16x32_bf16 v[48:51], v[136:139], v[188:191], v[48:51]
	v_mfma_f32_16x16x32_bf16 v[44:47], v[128:131], v[196:199], v[44:47]
	v_mfma_f32_16x16x32_bf16 v[36:39], v[136:139], v[196:199], v[36:39]
	v_mfma_f32_16x16x32_bf16 v[20:23], v[128:131], v[208:211], v[20:23]
	v_mfma_f32_16x16x32_bf16 v[16:19], v[136:139], v[208:211], v[16:19]
	v_mfma_f32_16x16x32_bf16 v[60:63], v[132:135], v[184:187], v[60:63]
	v_mfma_f32_16x16x32_bf16 v[56:59], v[140:143], v[184:187], v[56:59]
	v_mfma_f32_16x16x32_bf16 v[52:55], v[132:135], v[192:195], v[52:55]
	v_mfma_f32_16x16x32_bf16 v[48:51], v[140:143], v[192:195], v[48:51]
	v_mfma_f32_16x16x32_bf16 v[44:47], v[132:135], v[204:207], v[44:47]
	v_mfma_f32_16x16x32_bf16 v[36:39], v[140:143], v[204:207], v[36:39]
	v_mfma_f32_16x16x32_bf16 v[20:23], v[132:135], v[212:215], v[20:23]
	v_mfma_f32_16x16x32_bf16 v[16:19], v[140:143], v[212:215], v[16:19]
	s_setprio 0
	s_setprio 1
	v_mfma_f32_16x16x32_bf16 v[40:43], v[164:167], v[180:183], v[40:43]
	v_mfma_f32_16x16x32_bf16 v[32:35], v[172:175], v[180:183], v[32:35]
	v_mfma_f32_16x16x32_bf16 v[28:31], v[164:167], v[188:191], v[28:31]
	v_mfma_f32_16x16x32_bf16 v[24:27], v[172:175], v[188:191], v[24:27]
	v_mfma_f32_16x16x32_bf16 v[12:15], v[164:167], v[196:199], v[12:15]
	v_mfma_f32_16x16x32_bf16 v[8:11], v[172:175], v[196:199], v[8:11]
	v_mfma_f32_16x16x32_bf16 v[4:7], v[164:167], v[208:211], v[4:7]
	v_mfma_f32_16x16x32_bf16 v[0:3], v[172:175], v[208:211], v[0:3]
	v_mfma_f32_16x16x32_bf16 v[40:43], v[168:171], v[184:187], v[40:43]
	v_mfma_f32_16x16x32_bf16 v[32:35], v[176:179], v[184:187], v[32:35]
	v_mfma_f32_16x16x32_bf16 v[28:31], v[168:171], v[192:195], v[28:31]
	v_mfma_f32_16x16x32_bf16 v[24:27], v[176:179], v[192:195], v[24:27]
	v_mfma_f32_16x16x32_bf16 v[12:15], v[168:171], v[204:207], v[12:15]
	v_mfma_f32_16x16x32_bf16 v[8:11], v[176:179], v[204:207], v[8:11]
	v_mfma_f32_16x16x32_bf16 v[4:7], v[168:171], v[212:215], v[4:7]
	v_mfma_f32_16x16x32_bf16 v[0:3], v[176:179], v[212:215], v[0:3]
	s_setprio 0
	s_barrier
	s_add_i32 s64, 0, 0x18000
	s_add_i32 s65, 0, 0x1c000
	v_add_u32_e32 v140, s64, v159
	v_add_u32_e32 v176, s65, v159
	ds_read_b128 v[128:131], v140
	ds_read_b128 v[132:135], v140 offset:1024
	ds_read_b128 v[136:139], v140 offset:2048
	ds_read_b128 v[140:143], v140 offset:3072
	ds_read_b128 v[164:167], v176
	ds_read_b128 v[168:171], v176 offset:1024
	ds_read_b128 v[172:175], v176 offset:2048
	ds_read_b128 v[176:179], v176 offset:3072
	s_add_u32 s36, s36, 0x40000
	s_addc_u32 s37, s37, 0
	s_mov_b32 m0, s44
	v_lshl_add_u64 v[220:221], s[36:37], 0, v[150:151]
	ds_read_b128 v[180:183], v163 offset:32768
	ds_read_b128 v[184:187], v163 offset:33792
	ds_read_b128 v[188:191], v163 offset:34816
	ds_read_b128 v[192:195], v163 offset:35840
	ds_read_b128 v[196:199], v163 offset:36864
	ds_read_b128 v[204:207], v163 offset:37888
	ds_read_b128 v[208:211], v163 offset:38912
	ds_read_b128 v[212:215], v163 offset:39936
	global_load_lds_dwordx4 v[220:221], off
	v_lshl_add_u64 v[220:221], s[36:37], 0, v[148:149]
	s_mov_b32 m0, s45
	s_nop 0
	global_load_lds_dwordx4 v[220:221], off
	s_waitcnt vmcnt(8)
	s_waitcnt lgkmcnt(0)
	s_barrier
	s_setprio 1
	s_waitcnt lgkmcnt(0)
	v_mfma_f32_16x16x32_bf16 v[124:127], v[128:131], v[180:183], v[124:127]
	v_mfma_f32_16x16x32_bf16 v[120:123], v[136:139], v[180:183], v[120:123]
	v_mfma_f32_16x16x32_bf16 v[116:119], v[128:131], v[188:191], v[116:119]
	v_mfma_f32_16x16x32_bf16 v[112:115], v[136:139], v[188:191], v[112:115]
	v_mfma_f32_16x16x32_bf16 v[108:111], v[128:131], v[196:199], v[108:111]
	v_mfma_f32_16x16x32_bf16 v[100:103], v[136:139], v[196:199], v[100:103]
	v_mfma_f32_16x16x32_bf16 v[92:95], v[128:131], v[208:211], v[92:95]
	v_mfma_f32_16x16x32_bf16 v[80:83], v[136:139], v[208:211], v[80:83]
	v_mfma_f32_16x16x32_bf16 v[124:127], v[132:135], v[184:187], v[124:127]
	v_mfma_f32_16x16x32_bf16 v[120:123], v[140:143], v[184:187], v[120:123]
	v_mfma_f32_16x16x32_bf16 v[116:119], v[132:135], v[192:195], v[116:119]
	v_mfma_f32_16x16x32_bf16 v[112:115], v[140:143], v[192:195], v[112:115]
	v_mfma_f32_16x16x32_bf16 v[108:111], v[132:135], v[204:207], v[108:111]
	v_mfma_f32_16x16x32_bf16 v[100:103], v[140:143], v[204:207], v[100:103]
	v_mfma_f32_16x16x32_bf16 v[92:95], v[132:135], v[212:215], v[92:95]
	v_mfma_f32_16x16x32_bf16 v[80:83], v[140:143], v[212:215], v[80:83]
	s_setprio 0
	s_setprio 1
	v_mfma_f32_16x16x32_bf16 v[104:107], v[164:167], v[180:183], v[104:107]
	v_mfma_f32_16x16x32_bf16 v[96:99], v[172:175], v[180:183], v[96:99]
	v_mfma_f32_16x16x32_bf16 v[88:91], v[164:167], v[188:191], v[88:91]
	v_mfma_f32_16x16x32_bf16 v[84:87], v[172:175], v[188:191], v[84:87]
	v_mfma_f32_16x16x32_bf16 v[76:79], v[164:167], v[196:199], v[76:79]
	v_mfma_f32_16x16x32_bf16 v[72:75], v[172:175], v[196:199], v[72:75]
	v_mfma_f32_16x16x32_bf16 v[68:71], v[164:167], v[208:211], v[68:71]
	v_mfma_f32_16x16x32_bf16 v[64:67], v[172:175], v[208:211], v[64:67]
	v_mfma_f32_16x16x32_bf16 v[104:107], v[168:171], v[184:187], v[104:107]
	v_mfma_f32_16x16x32_bf16 v[96:99], v[176:179], v[184:187], v[96:99]
	v_mfma_f32_16x16x32_bf16 v[88:91], v[168:171], v[192:195], v[88:91]
	v_mfma_f32_16x16x32_bf16 v[84:87], v[176:179], v[192:195], v[84:87]
	v_mfma_f32_16x16x32_bf16 v[76:79], v[168:171], v[204:207], v[76:79]
	v_mfma_f32_16x16x32_bf16 v[72:75], v[176:179], v[204:207], v[72:75]
	v_mfma_f32_16x16x32_bf16 v[68:71], v[168:171], v[212:215], v[68:71]
	v_mfma_f32_16x16x32_bf16 v[64:67], v[176:179], v[212:215], v[64:67]
	s_setprio 0
	s_barrier
; #define PG8_STAGE(bufoff, gbase, voff) do { _Pragma("unroll") for (int _i = 0; _i < 2; ++_i) \
;         __builtin_amdgcn_global_load_lds((const unsigned*)((const char*)(gbase) + (voff)[_i]), (PG8_LAS unsigned*)(lds + (bufoff) + ldsw + _i * 8192), 16, 0, 0); } while (0)
; #define PG8_LDA(dst, b, h) do { _Pragma("unroll") for (int m = 0; m < 4; ++m) _Pragma("unroll") for (int k = 0; k < 2; ++k) dst[m][k] = *(const PG8_LAS bf16x8*)(lds + PG8_SA(b, h) + aoff + m * 2048 + k * 1024); } while (0)
; #define PG8_MMA(ai, bj, At, Bt) do { __builtin_amdgcn_s_setprio(1); _Pragma("unroll") for (int m = 0; m < 4; ++m) _Pragma("unroll") for (int n = 0; n < 2; ++n) _Pragma("unroll") for (int k = 0; k < 2; ++k) \
;         acc[ai][bj][m][n] = __builtin_amdgcn_mfma_f32_16x16x32_bf16(Bt[n][k], At[m][k], acc[ai][bj][m][n], 0, 0, 0); __builtin_amdgcn_s_setprio(0); } while (0)
; #define PG8_WAIT_V(n) asm volatile("s_waitcnt vmcnt(" #n ")" ::: "memory")
; #define PG8_BAR __builtin_amdgcn_s_barrier()
; template <class Epi, class Sched, bool ALIGN_EPI = false, bool SP2 = false>
; __device__ __forceinline__ void gemm_phase(PG8_LAS unsigned char* lds, const Gemm g, const Sched& S, const Epi& E) {
;     ...
;             PG8_LDA(At, 1, 1); PG8_STAGE(PG8_SB(1, 0), b3, voffB); PG8_STAGE(PG8_SB(1, 1), b3 + hstep, voffB); PG8_STAGE(PG8_SA(1, 0), a3, voffA);
;             PG8_WAIT_V(8); PG8_WAIT_L(0); PG8_BAR; PG8_MMA(1, 0, At, B0); PG8_MMA(1, 1, At, B1); PG8_BAR; PG8_SCHED;
;     __device__ __forceinline__ void operator()(const f32x4 (&acc)[2][2][4][2], const pg8::Unit& u, int wr, int wc, int fr, int fq) const {
;         const int row0 = u.pm * 256 + wr * 64 + fr, col0 = u.pn * 256 + wc * 32 + 4 * fq;
;         const float* gp = gatev + (size_t)(u.pm >> 3) * 3072 + col0;
;         f32x4 gv[2][2];
; #pragma unroll
;         for (int bj = 0; bj < 2; ++bj)
; #pragma unroll
;             for (int n = 0; n < 2; ++n) gv[bj][n] = *(const f32x4*)(gp + bj * 128 + n * 16);
; #pragma unroll
;         for (int ai = 0; ai < 2; ++ai)
; #pragma unroll
;             for (int m = 0; m < 4; ++m) {
;                 const size_t off = (size_t)(row0 + ai * 128 + m * 16) * DM + col0;
; #pragma unroll
;                 for (int bj = 0; bj < 2; ++bj)
; #pragma unroll
;                     for (int n = 0; n < 2; ++n) {
;                         const f32x4 xv = *(const f32x4*)(xin + off + bj * 128 + n * 16);
	s_add_i32 s36, s64, s42
	v_lshl_add_u64 v[156:157], v[156:157], 0, s[6:7]
	s_mov_b32 m0, s36
	ds_read_b128 v[180:183], v163 offset:49152
	ds_read_b128 v[184:187], v163 offset:50176
	ds_read_b128 v[188:191], v163 offset:51200
	ds_read_b128 v[192:195], v163 offset:52224
	ds_read_b128 v[196:199], v163 offset:53248
	ds_read_b128 v[204:207], v163 offset:54272
	ds_read_b128 v[208:211], v163 offset:55296
	ds_read_b128 v[212:215], v163 offset:56320
	global_load_lds_dwordx4 v[156:157], off
	s_add_i32 m0, s36, 0x2000
	s_add_u32 s34, s34, 0x40080
	v_lshl_add_u64 v[156:157], v[200:201], 0, s[6:7]
	s_addc_u32 s35, s35, 0
	s_add_i32 s36, s65, s42
	global_load_lds_dwordx4 v[156:157], off
	v_lshl_add_u64 v[156:157], s[34:35], 0, v[144:145]
	s_mov_b32 m0, s36
	s_nop 0
	global_load_lds_dwordx4 v[156:157], off
	v_lshl_add_u64 v[156:157], s[34:35], 0, v[146:147]
	s_add_i32 m0, s36, 0x2000
	s_nop 0
	global_load_lds_dwordx4 v[156:157], off
	v_lshl_add_u64 v[156:157], v[216:217], 0, s[6:7]
	s_mov_b32 m0, s49
	s_nop 0
	global_load_lds_dwordx4 v[156:157], off
	v_lshl_add_u64 v[156:157], v[218:219], 0, s[6:7]
	s_mov_b32 m0, s50
	s_nop 0
	global_load_lds_dwordx4 v[156:157], off
	s_waitcnt vmcnt(8)
	s_waitcnt lgkmcnt(0)
	s_barrier
	s_setprio 1
	s_waitcnt lgkmcnt(0)
	v_mfma_f32_16x16x32_bf16 v[60:63], v[128:131], v[180:183], v[60:63]
	v_mfma_f32_16x16x32_bf16 v[56:59], v[136:139], v[180:183], v[56:59]
	v_mfma_f32_16x16x32_bf16 v[52:55], v[128:131], v[188:191], v[52:55]
	v_mfma_f32_16x16x32_bf16 v[48:51], v[136:139], v[188:191], v[48:51]
	v_mfma_f32_16x16x32_bf16 v[44:47], v[128:131], v[196:199], v[44:47]
	v_mfma_f32_16x16x32_bf16 v[36:39], v[136:139], v[196:199], v[36:39]
	v_mfma_f32_16x16x32_bf16 v[20:23], v[128:131], v[208:211], v[20:23]
	v_mfma_f32_16x16x32_bf16 v[16:19], v[136:139], v[208:211], v[16:19]
	v_mfma_f32_16x16x32_bf16 v[60:63], v[132:135], v[184:187], v[60:63]
	v_mfma_f32_16x16x32_bf16 v[56:59], v[140:143], v[184:187], v[56:59]
	v_mfma_f32_16x16x32_bf16 v[52:55], v[132:135], v[192:195], v[52:55]
	v_mfma_f32_16x16x32_bf16 v[48:51], v[140:143], v[192:195], v[48:51]
	v_mfma_f32_16x16x32_bf16 v[44:47], v[132:135], v[204:207], v[44:47]
	v_mfma_f32_16x16x32_bf16 v[36:39], v[140:143], v[204:207], v[36:39]
	v_mfma_f32_16x16x32_bf16 v[20:23], v[132:135], v[212:215], v[20:23]
	v_mfma_f32_16x16x32_bf16 v[16:19], v[140:143], v[212:215], v[16:19]
	s_setprio 0
	s_setprio 1
	v_mfma_f32_16x16x32_bf16 v[40:43], v[164:167], v[180:183], v[40:43]
	v_mfma_f32_16x16x32_bf16 v[32:35], v[172:175], v[180:183], v[32:35]
	v_mfma_f32_16x16x32_bf16 v[28:31], v[164:167], v[188:191], v[28:31]
	v_mfma_f32_16x16x32_bf16 v[24:27], v[172:175], v[188:191], v[24:27]
	v_mfma_f32_16x16x32_bf16 v[12:15], v[164:167], v[196:199], v[12:15]
	v_mfma_f32_16x16x32_bf16 v[8:11], v[172:175], v[196:199], v[8:11]
	v_mfma_f32_16x16x32_bf16 v[4:7], v[164:167], v[208:211], v[4:7]
	v_mfma_f32_16x16x32_bf16 v[0:3], v[172:175], v[208:211], v[0:3]
	v_mfma_f32_16x16x32_bf16 v[40:43], v[168:171], v[184:187], v[40:43]
	v_mfma_f32_16x16x32_bf16 v[32:35], v[176:179], v[184:187], v[32:35]
	v_mfma_f32_16x16x32_bf16 v[28:31], v[168:171], v[192:195], v[28:31]
	v_mfma_f32_16x16x32_bf16 v[24:27], v[176:179], v[192:195], v[24:27]
	v_mfma_f32_16x16x32_bf16 v[12:15], v[168:171], v[204:207], v[12:15]
	v_mfma_f32_16x16x32_bf16 v[8:11], v[176:179], v[204:207], v[8:11]
	v_mfma_f32_16x16x32_bf16 v[4:7], v[168:171], v[212:215], v[4:7]
	v_mfma_f32_16x16x32_bf16 v[0:3], v[176:179], v[212:215], v[0:3]
	s_setprio 0
	s_barrier
	s_add_i32 s63, s63, 2
	s_add_u32 s61, s61, 0x100
	s_addc_u32 s62, s62, 0
	s_add_u32 s30, s30, 0x100
	s_addc_u32 s31, s31, 0
	s_cmp_gt_u32 s63, 13
	s_cbranch_scc0 .LBB0_1104
	s_and_b64 vcc, exec, s[10:11]
	s_cbranch_vccz .LBB0_1107
	s_barrier
.LBB0_1107:
	s_ashr_i32 s21, s28, 3
	v_lshl_or_b32 v128, s58, 8, v160
	s_mul_hi_i32 s23, s21, 0x3000
	s_mulk_i32 s21, 0x3000
	v_lshl_add_u32 v216, s28, 8, v158
	s_add_u32 s30, s47, s21
	v_ashrrev_i32_e32 v129, 31, v128
	s_addc_u32 s31, s48, s23
	v_lshlrev_b64 v[200:201], 2, v[128:129]
	v_lshl_add_u64 v[136:137], s[30:31], 0, v[200:201]
	v_and_b32_e32 v165, 0xffffff00, v216
	v_and_b32_e32 v166, 15, v216
	v_lshl_add_u32 v165, v166, 3, v165
	v_bfe_u32 v166, v216, 6, 1
	v_lshl_add_u32 v165, v166, 2, v165
	v_lshlrev_b32_e32 v156, 12, v165
	v_add_u32_e32 v156, v156, v200
	global_load_dwordx4 v[132:135], v[136:137], off
	global_load_dwordx4 v[128:131], v[136:137], off offset:64
	global_load_dwordx4 v[140:143], v[136:137], off offset:512
	s_nop 0
	global_load_dwordx4 v[136:139], v[136:137], off offset:576
	s_andn2_b64 vcc, exec, s[0:1]
	s_mov_b64 s[0:1], -1
	s_mov_b64 s[34:35], s[4:5]
	global_load_dwordx4 v[164:167], v156, s[34:35]
	global_load_dwordx4 v[168:171], v156, s[34:35] offset:64
	global_load_dwordx4 v[172:175], v156, s[34:35] offset:512
	global_load_dwordx4 v[176:179], v156, s[34:35] offset:576
	s_add_u32 s34, s4, 0x1000
	s_addc_u32 s35, s5, 0
	global_load_dwordx4 v[180:183], v156, s[34:35]
	global_load_dwordx4 v[184:187], v156, s[34:35] offset:64
	global_load_dwordx4 v[188:191], v156, s[34:35] offset:512
	global_load_dwordx4 v[192:195], v156, s[34:35] offset:576
	s_add_u32 s34, s4, 0x2000
	s_addc_u32 s35, s5, 0
	global_load_dwordx4 v[196:199], v156, s[34:35]
	global_load_dwordx4 v[204:207], v156, s[34:35] offset:64
	global_load_dwordx4 v[208:211], v156, s[34:35] offset:512
	global_load_dwordx4 v[212:215], v156, s[34:35] offset:576
	s_waitcnt vmcnt(8)
;     __device__ __forceinline__ void operator()(const f32x4 (&acc)[2][2][4][2], const pg8::Unit& u, int wr, int wc, int fr, int fq) const {
;     ...
;         for (int ai = 0; ai < 2; ++ai)
; #pragma unroll
;             for (int m = 0; m < 4; ++m) {
;                 const size_t off = (size_t)(row0 + ai * 128 + m * 16) * DM + col0;
; #pragma unroll
;                 for (int bj = 0; bj < 2; ++bj)
; #pragma unroll
;                     for (int n = 0; n < 2; ++n) {
;                         const f32x4 xv = *(const f32x4*)(xin + off + bj * 128 + n * 16);
;                         *(f32x4*)(out + off + bj * 128 + n * 16) = xv + gv[bj][n] * acc[ai][bj][m][n];
;                     }
	v_pk_fma_f32 v[166:167], v[126:127], v[134:135], v[166:167]
	v_pk_fma_f32 v[164:165], v[124:125], v[132:133], v[164:165]
	v_pk_fma_f32 v[170:171], v[122:123], v[130:131], v[170:171]
	v_pk_fma_f32 v[168:169], v[120:121], v[128:129], v[168:169]
	v_pk_fma_f32 v[174:175], v[106:107], v[142:143], v[174:175]
	v_pk_fma_f32 v[172:173], v[104:105], v[140:141], v[172:173]
	v_pk_fma_f32 v[178:179], v[98:99], v[138:139], v[178:179]
	v_pk_fma_f32 v[176:177], v[96:97], v[136:137], v[176:177]
	s_mov_b64 s[36:37], s[4:5]
	global_store_dwordx4 v156, v[164:167], s[36:37]
	global_store_dwordx4 v156, v[168:171], s[36:37] offset:64
	global_store_dwordx4 v156, v[172:175], s[36:37] offset:512
	global_store_dwordx4 v156, v[176:179], s[36:37] offset:576
	s_add_u32 s34, s4, 0x3000
	s_addc_u32 s35, s5, 0
	global_load_dwordx4 v[164:167], v156, s[34:35]
	global_load_dwordx4 v[168:171], v156, s[34:35] offset:64
	global_load_dwordx4 v[172:175], v156, s[34:35] offset:512
	global_load_dwordx4 v[176:179], v156, s[34:35] offset:576
	s_waitcnt vmcnt(12)
	v_pk_fma_f32 v[182:183], v[118:119], v[134:135], v[182:183]
	v_pk_fma_f32 v[180:181], v[116:117], v[132:133], v[180:181]
	v_pk_fma_f32 v[186:187], v[114:115], v[130:131], v[186:187]
	v_pk_fma_f32 v[184:185], v[112:113], v[128:129], v[184:185]
	v_pk_fma_f32 v[190:191], v[90:91], v[142:143], v[190:191]
	v_pk_fma_f32 v[188:189], v[88:89], v[140:141], v[188:189]
	v_pk_fma_f32 v[194:195], v[86:87], v[138:139], v[194:195]
	v_pk_fma_f32 v[192:193], v[84:85], v[136:137], v[192:193]
	s_add_u32 s36, s4, 0x1000
	s_addc_u32 s37, s5, 0
	global_store_dwordx4 v156, v[180:183], s[36:37]
	global_store_dwordx4 v156, v[184:187], s[36:37] offset:64
	global_store_dwordx4 v156, v[188:191], s[36:37] offset:512
	global_store_dwordx4 v156, v[192:195], s[36:37] offset:576
	s_add_u32 s34, s4, 0x80000
	s_addc_u32 s35, s5, 0
	global_load_dwordx4 v[180:183], v156, s[34:35]
	global_load_dwordx4 v[184:187], v156, s[34:35] offset:64
	global_load_dwordx4 v[188:191], v156, s[34:35] offset:512
	global_load_dwordx4 v[192:195], v156, s[34:35] offset:576
	s_waitcnt vmcnt(16)
	v_pk_fma_f32 v[198:199], v[110:111], v[134:135], v[198:199]
	v_pk_fma_f32 v[196:197], v[108:109], v[132:133], v[196:197]
	v_pk_fma_f32 v[206:207], v[102:103], v[130:131], v[206:207]
	v_pk_fma_f32 v[204:205], v[100:101], v[128:129], v[204:205]
	v_pk_fma_f32 v[210:211], v[78:79], v[142:143], v[210:211]
	v_pk_fma_f32 v[208:209], v[76:77], v[140:141], v[208:209]
	v_pk_fma_f32 v[214:215], v[74:75], v[138:139], v[214:215]
	v_pk_fma_f32 v[212:213], v[72:73], v[136:137], v[212:213]
	s_add_u32 s36, s4, 0x2000
	s_addc_u32 s37, s5, 0
	global_store_dwordx4 v156, v[196:199], s[36:37]
	global_store_dwordx4 v156, v[204:207], s[36:37] offset:64
	global_store_dwordx4 v156, v[208:211], s[36:37] offset:512
	global_store_dwordx4 v156, v[212:215], s[36:37] offset:576
	s_add_u32 s34, s4, 0x81000
	s_addc_u32 s35, s5, 0
	global_load_dwordx4 v[196:199], v156, s[34:35]
	global_load_dwordx4 v[204:207], v156, s[34:35] offset:64
	global_load_dwordx4 v[208:211], v156, s[34:35] offset:512
	global_load_dwordx4 v[212:215], v156, s[34:35] offset:576
	s_waitcnt vmcnt(16)
	v_pk_fma_f32 v[166:167], v[94:95], v[134:135], v[166:167]
	v_pk_fma_f32 v[164:165], v[92:93], v[132:133], v[164:165]
	v_pk_fma_f32 v[170:171], v[82:83], v[130:131], v[170:171]
	v_pk_fma_f32 v[168:169], v[80:81], v[128:129], v[168:169]
	v_pk_fma_f32 v[174:175], v[70:71], v[142:143], v[174:175]
	v_pk_fma_f32 v[172:173], v[68:69], v[140:141], v[172:173]
	v_pk_fma_f32 v[178:179], v[66:67], v[138:139], v[178:179]
	v_pk_fma_f32 v[176:177], v[64:65], v[136:137], v[176:177]
	s_add_u32 s36, s4, 0x3000
	s_addc_u32 s37, s5, 0
	global_store_dwordx4 v156, v[164:167], s[36:37]
	global_store_dwordx4 v156, v[168:171], s[36:37] offset:64
	global_store_dwordx4 v156, v[172:175], s[36:37] offset:512
	global_store_dwordx4 v156, v[176:179], s[36:37] offset:576
	s_add_u32 s34, s4, 0x82000
	s_addc_u32 s35, s5, 0
	global_load_dwordx4 v[164:167], v156, s[34:35]
	global_load_dwordx4 v[168:171], v156, s[34:35] offset:64
	global_load_dwordx4 v[172:175], v156, s[34:35] offset:512
	global_load_dwordx4 v[176:179], v156, s[34:35] offset:576
	s_waitcnt vmcnt(16)
;     __device__ __forceinline__ void operator()(const f32x4 (&acc)[2][2][4][2], const pg8::Unit& u, int wr, int wc, int fr, int fq) const {
;     ...
;         for (int ai = 0; ai < 2; ++ai)
; #pragma unroll
;             for (int m = 0; m < 4; ++m) {
;                 const size_t off = (size_t)(row0 + ai * 128 + m * 16) * DM + col0;
; #pragma unroll
;                 for (int bj = 0; bj < 2; ++bj)
; #pragma unroll
;                     for (int n = 0; n < 2; ++n) {
;                         const f32x4 xv = *(const f32x4*)(xin + off + bj * 128 + n * 16);
;                         *(f32x4*)(out + off + bj * 128 + n * 16) = xv + gv[bj][n] * acc[ai][bj][m][n];
;                     }
	v_pk_fma_f32 v[182:183], v[62:63], v[134:135], v[182:183]
	v_pk_fma_f32 v[180:181], v[60:61], v[132:133], v[180:181]
	v_pk_fma_f32 v[186:187], v[58:59], v[130:131], v[186:187]
	v_pk_fma_f32 v[184:185], v[56:57], v[128:129], v[184:185]
	v_pk_fma_f32 v[190:191], v[42:43], v[142:143], v[190:191]
	v_pk_fma_f32 v[188:189], v[40:41], v[140:141], v[188:189]
	v_pk_fma_f32 v[194:195], v[34:35], v[138:139], v[194:195]
	v_pk_fma_f32 v[192:193], v[32:33], v[136:137], v[192:193]
	s_add_u32 s36, s4, 0x80000
	s_addc_u32 s37, s5, 0
	global_store_dwordx4 v156, v[180:183], s[36:37]
	global_store_dwordx4 v156, v[184:187], s[36:37] offset:64
	global_store_dwordx4 v156, v[188:191], s[36:37] offset:512
	global_store_dwordx4 v156, v[192:195], s[36:37] offset:576
	s_add_u32 s34, s4, 0x83000
	s_addc_u32 s35, s5, 0
	global_load_dwordx4 v[180:183], v156, s[34:35]
	global_load_dwordx4 v[184:187], v156, s[34:35] offset:64
	global_load_dwordx4 v[188:191], v156, s[34:35] offset:512
	global_load_dwordx4 v[192:195], v156, s[34:35] offset:576
	s_waitcnt vmcnt(16)
	v_pk_fma_f32 v[198:199], v[54:55], v[134:135], v[198:199]
	v_pk_fma_f32 v[196:197], v[52:53], v[132:133], v[196:197]
	v_pk_fma_f32 v[206:207], v[50:51], v[130:131], v[206:207]
	v_pk_fma_f32 v[204:205], v[48:49], v[128:129], v[204:205]
	v_pk_fma_f32 v[210:211], v[30:31], v[142:143], v[210:211]
	v_pk_fma_f32 v[208:209], v[28:29], v[140:141], v[208:209]
	v_pk_fma_f32 v[214:215], v[26:27], v[138:139], v[214:215]
	v_pk_fma_f32 v[212:213], v[24:25], v[136:137], v[212:213]
	s_add_u32 s36, s4, 0x81000
	s_addc_u32 s37, s5, 0
	global_store_dwordx4 v156, v[196:199], s[36:37]
	global_store_dwordx4 v156, v[204:207], s[36:37] offset:64
	global_store_dwordx4 v156, v[208:211], s[36:37] offset:512
	global_store_dwordx4 v156, v[212:215], s[36:37] offset:576
	s_waitcnt vmcnt(12)
	v_pk_fma_f32 v[166:167], v[46:47], v[134:135], v[166:167]
	v_pk_fma_f32 v[164:165], v[44:45], v[132:133], v[164:165]
	v_pk_fma_f32 v[170:171], v[38:39], v[130:131], v[170:171]
	v_pk_fma_f32 v[168:169], v[36:37], v[128:129], v[168:169]
	v_pk_fma_f32 v[174:175], v[14:15], v[142:143], v[174:175]
	v_pk_fma_f32 v[172:173], v[12:13], v[140:141], v[172:173]
	v_pk_fma_f32 v[178:179], v[10:11], v[138:139], v[178:179]
	v_pk_fma_f32 v[176:177], v[8:9], v[136:137], v[176:177]
	s_add_u32 s36, s4, 0x82000
	s_addc_u32 s37, s5, 0
	global_store_dwordx4 v156, v[164:167], s[36:37]
	global_store_dwordx4 v156, v[168:171], s[36:37] offset:64
	global_store_dwordx4 v156, v[172:175], s[36:37] offset:512
	global_store_dwordx4 v156, v[176:179], s[36:37] offset:576
	s_waitcnt vmcnt(8)
	v_pk_fma_f32 v[182:183], v[22:23], v[134:135], v[182:183]
	v_pk_fma_f32 v[180:181], v[20:21], v[132:133], v[180:181]
	v_pk_fma_f32 v[186:187], v[18:19], v[130:131], v[186:187]
	v_pk_fma_f32 v[184:185], v[16:17], v[128:129], v[184:185]
	v_pk_fma_f32 v[190:191], v[6:7], v[142:143], v[190:191]
	v_pk_fma_f32 v[188:189], v[4:5], v[140:141], v[188:189]
	v_pk_fma_f32 v[194:195], v[2:3], v[138:139], v[194:195]
	v_pk_fma_f32 v[192:193], v[0:1], v[136:137], v[192:193]
	s_add_u32 s36, s4, 0x83000
	s_addc_u32 s37, s5, 0
	global_store_dwordx4 v156, v[180:183], s[36:37]
	global_store_dwordx4 v156, v[184:187], s[36:37] offset:64
	global_store_dwordx4 v156, v[188:191], s[36:37] offset:512
	global_store_dwordx4 v156, v[192:195], s[36:37] offset:576
	s_cbranch_vccnz .LBB0_1096
	s_andn2_b64 vcc, exec, s[8:9]
	s_cbranch_vccnz .LBB0_1095
	s_barrier
	s_branch .LBB0_1095
